# stack: attention prefetch+remap, pool batching, EW1/EW2 load hoisting with preloaded gains, ew_init 4 rows per iteration, redundant acc zeroing removed, streaming stores write-through
# baseline (speedup 1.0000x reference)
; __device__ __forceinline__ void ew_post(const bf16* Y, const float* xin, float* xout, const float* gpost, const float* gnext, bf16* H, int gw, int ngw, int lane) {
;     for (int m0 = EW_NR * gw; m0 < NTOK; m0 += EW_NR * ngw) {
;         f32x4 y[EW_NR][4], xv[EW_NR][4]; float s[EW_NR];
; #pragma unroll
;         for (int q = 0; q < EW_NR; ++q) { const v2u* yr = (const v2u*)(Y + (size_t)(m0 + q) * DM) + lane; const f32x4* xr = (const f32x4*)(xin + (size_t)(m0 + q) * DM) + lane;
; #pragma unroll
;             for (int j = 0; j < 4; ++j) { const v2u w = __builtin_nontemporal_load(yr + 64 * j); y[q][j] = (f32x4){bf_lo(w.x), bf_hi(w.x), bf_lo(w.y), bf_hi(w.y)}; xv[q][j] = __builtin_nontemporal_load(xr + 64 * j); } }
; #pragma unroll
;         for (int q = 0; q < EW_NR; ++q) { s[q] = 0.f;
; #pragma unroll
;             for (int j = 0; j < 4; ++j) s[q] += (y[q][j].x * y[q][j].x + y[q][j].y * y[q][j].y) + (y[q][j].z * y[q][j].z + y[q][j].w * y[q][j].w); }
.LBB0_191:
	global_load_dwordx2 v[16:17], v[68:69], off offset:-4096 nt
	global_load_dwordx2 v[18:19], v[68:69], off offset:-2048 nt
	global_load_dwordx2 v[20:21], v[68:69], off nt
	v_add_co_u32_e32 v0, vcc, 0xfffff000, v68
	s_movk_i32 s4, 0xf000
	s_nop 0
	v_addc_co_u32_e32 v1, vcc, -1, v69, vcc
	global_load_dwordx2 v[22:23], v[0:1], off offset:-2048 nt
	global_load_dwordx2 v[24:25], v[0:1], off offset:-3584 nt
	global_load_dwordx2 v[26:27], v[0:1], off offset:-3072 nt
	global_load_dwordx2 v[28:29], v[0:1], off offset:-2560 nt
	global_load_dwordx2 v[30:31], v[0:1], off offset:-1536 nt
	global_load_dwordx2 v[42:43], v[68:69], off offset:-3584 nt
	global_load_dwordx2 v[84:85], v[68:69], off offset:-3072 nt
	global_load_dwordx2 v[94:95], v[68:69], off offset:-2560 nt
	global_load_dwordx4 v[4:7], v[70:71], off offset:-3072 nt
	global_load_dwordx2 v[38:39], v[0:1], off offset:-1024 nt
	global_load_dwordx2 v[46:47], v[68:69], off offset:-1536 nt
	global_load_dwordx2 v[86:87], v[68:69], off offset:-1024 nt
	global_load_dwordx2 v[88:89], v[68:69], off offset:-512 nt
	global_load_dwordx2 v[40:41], v[0:1], off offset:-512 nt
	v_add_co_u32_e32 v36, vcc, s4, v70
	s_movk_i32 s6, 0xe000
	s_nop 0
	v_addc_co_u32_e32 v37, vcc, -1, v71, vcc
	v_add_co_u32_e32 v48, vcc, 0xffffd000, v70
	s_mov_b64 s[4:5], vcc
	v_addc_co_u32_e64 v49, s[4:5], -1, v71, s[4:5]
	global_load_dwordx4 v[0:3], v[48:49], off offset:-3072 nt
	v_add_co_u32_e32 v50, vcc, s6, v70
	global_load_dwordx4 v[8:11], v[36:37], off offset:-3072 nt
	s_nop 0
	v_addc_co_u32_e32 v51, vcc, -1, v71, vcc
	global_load_dwordx4 v[12:15], v[50:51], off offset:-3072 nt
	global_load_dwordx4 v[124:127], v[48:49], off offset:-2048 nt
	global_load_dwordx4 v[128:131], v[50:51], off offset:-2048 nt
	global_load_dwordx4 v[132:135], v[36:37], off offset:-2048 nt
	global_load_dwordx4 v[136:139], v[70:71], off offset:-2048 nt
	global_load_dwordx4 v[140:143], v[48:49], off offset:-1024 nt
	global_load_dwordx4 v[144:147], v[50:51], off offset:-1024 nt
	global_load_dwordx4 v[148:151], v[36:37], off offset:-1024 nt
	global_load_dwordx4 v[152:155], v[70:71], off offset:-1024 nt
	global_load_dwordx4 v[156:159], v[48:49], off nt
	global_load_dwordx4 v[160:163], v[70:71], off offset:-4096 nt
	global_load_dwordx4 v[164:167], v[50:51], off nt
	global_load_dwordx4 v[168:171], v[70:71], off nt
	s_waitcnt vmcnt(0)
	v_lshlrev_b32_e32 v79, 16, v22
	v_and_b32_e32 v59, 0xffff0000, v22
	v_lshlrev_b32_e32 v60, 16, v23
	v_and_b32_e32 v61, 0xffff0000, v23
	v_lshlrev_b32_e32 v54, 16, v17
	v_and_b32_e32 v55, 0xffff0000, v17
	v_lshlrev_b32_e32 v72, 16, v19
	v_and_b32_e32 v73, 0xffff0000, v19
	v_and_b32_e32 v17, 0xffff0000, v24
	v_and_b32_e32 v19, 0xffff0000, v25
	v_lshlrev_b32_e32 v83, 16, v16
	v_and_b32_e32 v53, 0xffff0000, v16
	v_lshlrev_b32_e32 v81, 16, v18
	v_and_b32_e32 v63, 0xffff0000, v18
	v_lshlrev_b32_e32 v16, 16, v24
	v_lshlrev_b32_e32 v18, 16, v25
	v_and_b32_e32 v23, 0xffff0000, v27
	v_and_b32_e32 v22, 0xffff0000, v26
	v_lshlrev_b32_e32 v32, 16, v28
	v_and_b32_e32 v33, 0xffff0000, v28
	v_mul_f32_e32 v24, v19, v19
	v_mul_f32_e32 v28, v17, v17
	v_mov_b32_e32 v25, v79
	v_lshlrev_b32_e32 v77, 16, v20
	v_and_b32_e32 v57, 0xffff0000, v20
	v_lshlrev_b32_e32 v74, 16, v21
	v_and_b32_e32 v75, 0xffff0000, v21
	v_lshlrev_b32_e32 v21, 16, v27
	v_lshlrev_b32_e32 v20, 16, v26
	v_lshlrev_b32_e32 v34, 16, v29
	v_and_b32_e32 v35, 0xffff0000, v29
	v_pk_mul_f32 v[26:27], v[22:23], v[22:23]
	v_pk_fma_f32 v[90:91], v[18:19], v[18:19], v[24:25] op_sel_hi:[1,1,0]
	v_pk_fma_f32 v[28:29], v[16:17], v[16:17], v[28:29] op_sel_hi:[1,1,0]
	v_mul_f32_e32 v44, v33, v33
	v_mul_f32_e32 v52, v35, v35
	v_pk_fma_f32 v[26:27], v[20:21], v[20:21], v[26:27]
	v_mov_b32_e32 v78, v28
	v_mov_b32_e32 v24, v90
	v_mul_f32_e32 v56, v59, v59
	v_mul_f32_e32 v58, v60, v60
	v_mul_f32_e32 v62, v61, v61
	v_pk_fma_f32 v[44:45], v[32:33], v[32:33], v[44:45] op_sel_hi:[1,1,0]
	v_pk_fma_f32 v[92:93], v[34:35], v[34:35], v[52:53] op_sel_hi:[1,1,0]
	v_pk_add_f32 v[28:29], v[28:29], v[90:91]
	v_pk_add_f32 v[26:27], v[26:27], v[26:27] op_sel:[0,1] op_sel_hi:[1,0]
	v_pk_mul_f32 v[24:25], v[78:79], v[24:25]
	v_mov_b32_e32 v45, v58
	v_mov_b32_e32 v27, v56
	v_mov_b32_e32 v29, v25
	v_mov_b32_e32 v93, v62
	v_pk_add_f32 v[24:25], v[28:29], v[26:27]
	v_pk_add_f32 v[26:27], v[44:45], v[92:93]
	v_and_b32_e32 v45, 0xffff0000, v30
	v_and_b32_e32 v93, 0xffff0000, v31
	v_pk_add_f32 v[102:103], v[24:25], v[26:27]
	v_lshlrev_b32_e32 v44, 16, v30
	v_lshlrev_b32_e32 v92, 16, v31
	v_mul_f32_e32 v24, v93, v93
	v_and_b32_e32 v27, 0xffff0000, v39
	v_and_b32_e32 v26, 0xffff0000, v38
	v_mul_f32_e32 v52, v45, v45
	v_pk_fma_f32 v[28:29], v[92:93], v[92:93], v[24:25] op_sel_hi:[1,1,0]
	v_lshlrev_b32_e32 v25, 16, v39
	v_lshlrev_b32_e32 v24, 16, v38
	v_pk_mul_f32 v[30:31], v[26:27], v[26:27]
	v_pk_fma_f32 v[90:91], v[44:45], v[44:45], v[52:53] op_sel_hi:[1,1,0]
	v_pk_fma_f32 v[30:31], v[24:25], v[24:25], v[30:31]
	v_mov_b32_e32 v82, v90
	v_mov_b32_e32 v96, v28
	v_mov_b32_e32 v97, v83
	v_mul_f32_e32 v56, v53, v53
	v_pk_add_f32 v[28:29], v[90:91], v[28:29]
	v_pk_mul_f32 v[90:91], v[82:83], v[96:97]
	v_pk_add_f32 v[30:31], v[30:31], v[30:31] op_sel:[0,1] op_sel_hi:[1,0]
	v_lshlrev_b32_e32 v38, 16, v40
	v_and_b32_e32 v39, 0xffff0000, v40
	v_lshlrev_b32_e32 v40, 16, v41
	v_and_b32_e32 v41, 0xffff0000, v41
	v_mov_b32_e32 v29, v91
	v_mov_b32_e32 v31, v56
	v_pk_add_f32 v[28:29], v[28:29], v[30:31]
	v_mul_f32_e32 v30, v39, v39
	v_mul_f32_e32 v52, v41, v41
	v_mul_f32_e32 v58, v54, v54
	v_mul_f32_e32 v62, v55, v55
	v_pk_fma_f32 v[30:31], v[38:39], v[38:39], v[30:31] op_sel_hi:[1,1,0]
	v_pk_fma_f32 v[90:91], v[40:41], v[40:41], v[52:53] op_sel_hi:[1,1,0]
; __device__ __forceinline__ void ew_post(const bf16* Y, const float* xin, float* xout, const float* gpost, const float* gnext, bf16* H, int gw, int ngw, int lane) {
;     ...
;         for (int q = 0; q < EW_NR; ++q) { const v2u* yr = (const v2u*)(Y + (size_t)(m0 + q) * DM) + lane; const f32x4* xr = (const f32x4*)(xin + (size_t)(m0 + q) * DM) + lane;
; #pragma unroll
;             for (int j = 0; j < 4; ++j) { const v2u w = __builtin_nontemporal_load(yr + 64 * j); y[q][j] = (f32x4){bf_lo(w.x), bf_hi(w.x), bf_lo(w.y), bf_hi(w.y)}; xv[q][j] = __builtin_nontemporal_load(xr + 64 * j); } }
; #pragma unroll
;         for (int q = 0; q < EW_NR; ++q) { s[q] = 0.f;
; #pragma unroll
;             for (int j = 0; j < 4; ++j) s[q] += (y[q][j].x * y[q][j].x + y[q][j].y * y[q][j].y) + (y[q][j].z * y[q][j].z + y[q][j].w * y[q][j].w); }
;         float rstd[EW_NR], s2[EW_NR];
; #pragma unroll
;         for (int q = 0; q < EW_NR; ++q) { rstd[q] = rsqrtf(wave_sum(s[q]) * (1.f / DM) + RMS_EPS); s2[q] = 0.f; }
; #pragma unroll
;         for (int j = 0; j < 4; ++j) { const f32x4 g = *((const f32x4*)gpost + lane + 64 * j);
; #pragma unroll
;             for (int q = 0; q < EW_NR; ++q) { xv[q][j] = xv[q][j] + y[q][j] * rstd[q] * g; __builtin_nontemporal_store(xv[q][j], (f32x4*)(xout + (size_t)(m0 + q) * DM) + lane + 64 * j);
;                 s2[q] += (xv[q][j].x * xv[q][j].x + xv[q][j].y * xv[q][j].y) + (xv[q][j].z * xv[q][j].z + xv[q][j].w * xv[q][j].w); } }
	v_mov_b32_e32 v31, v58
	v_mov_b32_e32 v91, v62
	v_pk_add_f32 v[30:31], v[30:31], v[90:91]
	v_and_b32_e32 v97, 0xffff0000, v43
	v_pk_add_f32 v[114:115], v[28:29], v[30:31]
	v_and_b32_e32 v91, 0xffff0000, v42
	v_lshlrev_b32_e32 v96, 16, v43
	v_mul_f32_e32 v28, v97, v97
	v_and_b32_e32 v31, 0xffff0000, v85
	v_and_b32_e32 v30, 0xffff0000, v84
	v_lshlrev_b32_e32 v90, 16, v42
	v_pk_fma_f32 v[98:99], v[96:97], v[96:97], v[28:29] op_sel_hi:[1,1,0]
	v_lshlrev_b32_e32 v29, 16, v85
	v_lshlrev_b32_e32 v28, 16, v84
	v_pk_mul_f32 v[42:43], v[30:31], v[30:31]
	v_mul_f32_e32 v52, v91, v91
	v_pk_fma_f32 v[100:101], v[28:29], v[28:29], v[42:43]
	v_lshlrev_b32_e32 v42, 16, v94
	v_and_b32_e32 v43, 0xffff0000, v94
	v_lshlrev_b32_e32 v84, 16, v95
	v_and_b32_e32 v85, 0xffff0000, v95
	v_pk_fma_f32 v[94:95], v[90:91], v[90:91], v[52:53] op_sel_hi:[1,1,0]
	v_mov_b32_e32 v110, v98
	v_mov_b32_e32 v80, v94
	v_mov_b32_e32 v111, v81
	v_pk_add_f32 v[94:95], v[94:95], v[98:99]
	v_pk_mul_f32 v[98:99], v[80:81], v[110:111]
	s_nop 1
	v_mov_b32_e32 v110, v192
	v_mov_b32_e32 v111, v193
	v_mov_b32_e32 v112, v194
	v_mov_b32_e32 v113, v195
	v_mul_f32_e32 v56, v63, v63
	v_mov_b32_e32 v95, v99
	v_pk_add_f32 v[98:99], v[100:101], v[100:101] op_sel:[0,1] op_sel_hi:[1,0]
	v_mul_f32_e32 v52, v43, v43
	v_mov_b32_e32 v99, v56
	v_pk_add_f32 v[94:95], v[94:95], v[98:99]
	v_pk_fma_f32 v[98:99], v[42:43], v[42:43], v[52:53] op_sel_hi:[1,1,0]
	v_mul_f32_e32 v52, v85, v85
	v_mul_f32_e32 v58, v72, v72
	v_mul_f32_e32 v62, v73, v73
	v_pk_fma_f32 v[100:101], v[84:85], v[84:85], v[52:53] op_sel_hi:[1,1,0]
	v_mov_b32_e32 v99, v58
	v_mov_b32_e32 v101, v62
	v_pk_add_f32 v[98:99], v[98:99], v[100:101]
	v_and_b32_e32 v101, 0xffff0000, v47
	v_pk_add_f32 v[116:117], v[94:95], v[98:99]
	v_and_b32_e32 v99, 0xffff0000, v46
	v_lshlrev_b32_e32 v98, 16, v46
	v_lshlrev_b32_e32 v100, 16, v47
	v_mul_f32_e32 v46, v101, v101
	v_mul_f32_e32 v52, v99, v99
	v_pk_fma_f32 v[118:119], v[100:101], v[100:101], v[46:47] op_sel_hi:[1,1,0]
	v_pk_fma_f32 v[122:123], v[98:99], v[98:99], v[52:53] op_sel_hi:[1,1,0]
	v_and_b32_e32 v95, 0xffff0000, v87
	v_mov_b32_e32 v76, v122
	v_pk_add_f32 v[122:123], v[122:123], v[118:119]
	v_mov_b32_e32 v119, v77
	v_pk_mul_f32 v[118:119], v[76:77], v[118:119]
	v_and_b32_e32 v94, 0xffff0000, v86
	v_mov_b32_e32 v123, v119
	v_mov_b32_e32 v118, v114
	v_mov_b32_e32 v119, v102
	v_mov_b32_e32 v102, v115
	v_pk_add_f32 v[102:103], v[118:119], v[102:103]
	ds_bpermute_b32 v115, v104, v103
	ds_bpermute_b32 v114, v104, v102
	v_lshlrev_b32_e32 v47, 16, v87
	v_lshlrev_b32_e32 v46, 16, v86
	v_pk_mul_f32 v[86:87], v[94:95], v[94:95]
	v_mul_f32_e32 v56, v57, v57
	v_pk_fma_f32 v[120:121], v[46:47], v[46:47], v[86:87]
	v_and_b32_e32 v87, 0xffff0000, v88
	s_waitcnt lgkmcnt(0)
	v_pk_add_f32 v[102:103], v[102:103], v[114:115]
	v_lshlrev_b32_e32 v86, 16, v88
	v_lshlrev_b32_e32 v88, 16, v89
	v_and_b32_e32 v89, 0xffff0000, v89
	v_pk_add_f32 v[118:119], v[120:121], v[120:121] op_sel:[0,1] op_sel_hi:[1,0]
	ds_bpermute_b32 v115, v105, v103
	ds_bpermute_b32 v114, v105, v102
	v_mul_f32_e32 v52, v87, v87
	v_mov_b32_e32 v119, v56
	v_pk_fma_f32 v[120:121], v[86:87], v[86:87], v[52:53] op_sel_hi:[1,1,0]
	v_mul_f32_e32 v52, v89, v89
	v_mul_f32_e32 v58, v74, v74
	v_mul_f32_e32 v62, v75, v75
	v_pk_add_f32 v[118:119], v[122:123], v[118:119]
	v_pk_fma_f32 v[122:123], v[88:89], v[88:89], v[52:53] op_sel_hi:[1,1,0]
	v_mov_b32_e32 v121, v58
	v_mov_b32_e32 v123, v62
	v_pk_add_f32 v[120:121], v[120:121], v[122:123]
	s_waitcnt lgkmcnt(0)
	v_pk_add_f32 v[102:103], v[102:103], v[114:115]
	v_pk_add_f32 v[118:119], v[118:119], v[120:121]
	ds_bpermute_b32 v115, v106, v103
	ds_bpermute_b32 v114, v106, v102
	v_mov_b32_e32 v120, v118
	v_mov_b32_e32 v121, v116
	v_mov_b32_e32 v116, v119
	v_pk_add_f32 v[116:117], v[120:121], v[116:117]
	ds_bpermute_b32 v119, v104, v117
	ds_bpermute_b32 v118, v104, v116
	s_waitcnt lgkmcnt(2)
	v_pk_add_f32 v[102:103], v[102:103], v[114:115]
	ds_bpermute_b32 v115, v107, v103
	ds_bpermute_b32 v114, v107, v102
	v_mov_b32_e32 v62, v81
	s_waitcnt lgkmcnt(2)
	v_pk_add_f32 v[118:119], v[116:117], v[118:119]
	ds_bpermute_b32 v121, v105, v119
	ds_bpermute_b32 v120, v105, v118
	s_waitcnt lgkmcnt(2)
	v_pk_add_f32 v[102:103], v[102:103], v[114:115]
	ds_bpermute_b32 v115, v108, v103
	ds_bpermute_b32 v114, v108, v102
	s_waitcnt lgkmcnt(2)
	v_pk_add_f32 v[118:119], v[118:119], v[120:121]
	ds_bpermute_b32 v121, v106, v119
	ds_bpermute_b32 v120, v106, v118
	s_waitcnt lgkmcnt(2)
	v_pk_add_f32 v[102:103], v[102:103], v[114:115]
	ds_bpermute_b32 v123, v109, v103
	ds_bpermute_b32 v122, v109, v102
	s_nop 1
	v_mov_b32_e32 v114, v124
	v_mov_b32_e32 v115, v125
	v_mov_b32_e32 v116, v126
	v_mov_b32_e32 v117, v127
	s_waitcnt lgkmcnt(2)
	v_pk_add_f32 v[118:119], v[118:119], v[120:121]
	ds_bpermute_b32 v121, v107, v119
	ds_bpermute_b32 v120, v107, v118
	s_waitcnt lgkmcnt(2)
	v_pk_add_f32 v[102:103], v[102:103], v[122:123]
	v_mov_b64_e32 v[122:123], s[24:25]
	v_pk_fma_f32 v[102:103], v[102:103], s[44:45], v[122:123] op_sel_hi:[1,0,0]
	s_waitcnt lgkmcnt(0)
	v_pk_add_f32 v[118:119], v[118:119], v[120:121]
	v_mul_f32_e32 v52, 0x4b800000, v103
	v_cmp_gt_f32_e32 vcc, s3, v103
	ds_bpermute_b32 v121, v108, v119
	ds_bpermute_b32 v120, v108, v118
	v_cndmask_b32_e32 v52, v103, v52, vcc
	v_rsq_f32_e32 v52, v52
	v_mul_f32_e32 v56, 0x4b800000, v102
	v_cmp_gt_f32_e64 s[4:5], s3, v102
	v_mul_f32_e32 v58, 0x45800000, v52
	s_nop 0
	v_cndmask_b32_e64 v56, v102, v56, s[4:5]
	s_waitcnt lgkmcnt(0)
; __device__ __forceinline__ void ew_post(const bf16* Y, const float* xin, float* xout, const float* gpost, const float* gnext, bf16* H, int gw, int ngw, int lane) {
;     ...
;         for (int q = 0; q < EW_NR; ++q) { rstd[q] = rsqrtf(wave_sum(s[q]) * (1.f / DM) + RMS_EPS); s2[q] = 0.f; }
; #pragma unroll
;         for (int j = 0; j < 4; ++j) { const f32x4 g = *((const f32x4*)gpost + lane + 64 * j);
; #pragma unroll
;             for (int q = 0; q < EW_NR; ++q) { xv[q][j] = xv[q][j] + y[q][j] * rstd[q] * g; __builtin_nontemporal_store(xv[q][j], (f32x4*)(xout + (size_t)(m0 + q) * DM) + lane + 64 * j);
;                 s2[q] += (xv[q][j].x * xv[q][j].x + xv[q][j].y * xv[q][j].y) + (xv[q][j].z * xv[q][j].z + xv[q][j].w * xv[q][j].w); } }
	v_pk_add_f32 v[102:103], v[118:119], v[120:121]
	v_cndmask_b32_e32 v76, v52, v58, vcc
	v_rsq_f32_e32 v52, v56
	ds_bpermute_b32 v119, v109, v103
	ds_bpermute_b32 v118, v109, v102
	v_pk_mul_f32 v[16:17], v[76:77], v[16:17] op_sel_hi:[0,1]
	v_pk_fma_f32 v[0:1], v[16:17], v[110:111], v[0:1]
	v_mul_f32_e32 v16, 0x45800000, v52
	v_cndmask_b32_e64 v78, v52, v16, s[4:5]
	s_waitcnt lgkmcnt(0)
	v_pk_add_f32 v[16:17], v[102:103], v[118:119]
	v_pk_mul_f32 v[18:19], v[76:77], v[18:19] op_sel_hi:[0,1]
	v_pk_fma_f32 v[16:17], v[16:17], s[44:45], v[122:123] op_sel_hi:[1,0,0]
	v_pk_fma_f32 v[2:3], v[18:19], v[112:113], v[2:3]
	v_mul_f32_e32 v18, 0x4b800000, v17
	v_cmp_gt_f32_e32 vcc, s3, v17
	s_nop 1
	v_mov_b32_e32 v118, v128
	v_mov_b32_e32 v119, v129
	v_mov_b32_e32 v120, v130
	v_mov_b32_e32 v121, v131
	v_pk_mul_f32 v[34:35], v[76:77], v[34:35] op_sel_hi:[0,1]
	v_cndmask_b32_e32 v17, v17, v18, vcc
	v_rsq_f32_e32 v17, v17
	v_pk_mul_f32 v[18:19], v[78:79], v[44:45] op_sel_hi:[0,1]
	v_pk_fma_f32 v[12:13], v[18:19], v[110:111], v[12:13]
	v_pk_mul_f32 v[44:45], v[78:79], v[92:93] op_sel_hi:[0,1]
	v_mul_f32_e32 v18, 0x45800000, v17
	v_cndmask_b32_e32 v80, v17, v18, vcc
	v_mul_f32_e32 v17, 0x4b800000, v16
	v_cmp_gt_f32_e32 vcc, s3, v16
	v_pk_fma_f32 v[14:15], v[44:45], v[112:113], v[14:15]
	v_pk_mul_f32 v[18:19], v[80:81], v[96:97] op_sel_hi:[0,1]
	v_cndmask_b32_e32 v16, v16, v17, vcc
	v_rsq_f32_e32 v44, v16
	v_pk_mul_f32 v[16:17], v[80:81], v[90:91] op_sel_hi:[0,1]
	s_nop 1
	v_mov_b32_e32 v90, v132
	v_mov_b32_e32 v91, v133
	v_mov_b32_e32 v92, v134
	v_mov_b32_e32 v93, v135
	v_pk_fma_f32 v[16:17], v[110:111], v[16:17], v[8:9]
	v_mul_f32_e32 v8, 0x45800000, v44
	v_cndmask_b32_e32 v82, v44, v8, vcc
	v_pk_fma_f32 v[18:19], v[112:113], v[18:19], v[10:11]
	v_pk_mul_f32 v[8:9], v[82:83], v[98:99] op_sel_hi:[0,1]
	v_pk_mul_f32 v[10:11], v[82:83], v[100:101] op_sel_hi:[0,1]
	global_store_dwordx4 v[48:49], v[0:3], off offset:-3072 sc0 sc1 nt
	global_store_dwordx4 v[50:51], v[12:15], off offset:-3072 sc0 sc1 nt
	global_store_dwordx4 v[36:37], v[16:19], off offset:-3072 sc0 sc1 nt
	v_pk_fma_f32 v[6:7], v[112:113], v[10:11], v[6:7]
	v_pk_fma_f32 v[4:5], v[110:111], v[8:9], v[4:5]
	s_nop 1
	v_mov_b32_e32 v96, v136
	v_mov_b32_e32 v97, v137
	v_mov_b32_e32 v98, v138
	v_mov_b32_e32 v99, v139
	v_mov_b32_e32 v8, v21
	global_store_dwordx4 v[70:71], v[4:7], off offset:-3072 sc0 sc1 nt
	s_nop 1
	v_mov_b32_e32 v100, v196
	v_mov_b32_e32 v101, v197
	v_mov_b32_e32 v102, v198
	v_mov_b32_e32 v103, v199
	s_nop 1
	v_mov_b32_e32 v110, v140
	v_mov_b32_e32 v111, v141
	v_mov_b32_e32 v112, v142
	v_mov_b32_e32 v113, v143
	v_mov_b32_e32 v9, v23
	v_mov_b32_e32 v21, v22
	v_pk_mul_f32 v[10:11], v[76:77], v[8:9] op_sel_hi:[0,1]
	v_pk_mul_f32 v[8:9], v[76:77], v[20:21] op_sel_hi:[0,1]
	v_mov_b32_e32 v20, v25
	v_mov_b32_e32 v21, v27
	v_mov_b32_e32 v25, v26
	v_pk_mul_f32 v[22:23], v[78:79], v[20:21] op_sel_hi:[0,1]
	v_pk_mul_f32 v[20:21], v[78:79], v[24:25] op_sel_hi:[0,1]
	v_mov_b32_e32 v24, v29
	v_mov_b32_e32 v25, v31
	v_mov_b32_e32 v29, v30
	v_pk_mul_f32 v[26:27], v[80:81], v[24:25] op_sel_hi:[0,1]
	v_pk_mul_f32 v[24:25], v[80:81], v[28:29] op_sel_hi:[0,1]
	v_mov_b32_e32 v28, v47
	v_mov_b32_e32 v29, v95
	v_mov_b32_e32 v47, v94
	v_pk_mul_f32 v[30:31], v[82:83], v[28:29] op_sel_hi:[0,1]
	v_pk_mul_f32 v[28:29], v[82:83], v[46:47] op_sel_hi:[0,1]
	v_pk_mul_f32 v[32:33], v[76:77], v[32:33] op_sel_hi:[0,1]
	v_pk_mul_f32 v[40:41], v[78:79], v[40:41] op_sel_hi:[0,1]
	v_pk_mul_f32 v[38:39], v[78:79], v[38:39] op_sel_hi:[0,1]
	v_mov_b32_e32 v56, v77
	v_mov_b32_e32 v58, v79
	v_mov_b32_e32 v52, v83
	v_pk_mul_f32 v[74:75], v[82:83], v[74:75] op_sel_hi:[0,1]
	v_pk_mul_f32 v[58:59], v[76:77], v[58:59] op_sel_hi:[0,1]
	v_pk_mul_f32 v[72:73], v[80:81], v[72:73] op_sel_hi:[0,1]
	v_pk_mul_f32 v[54:55], v[78:79], v[54:55] op_sel_hi:[0,1]
	v_pk_mul_f32 v[52:53], v[78:79], v[52:53] op_sel_hi:[0,1]
	s_andn2_b64 vcc, exec, s[20:21]
	v_pk_fma_f32 v[8:9], v[8:9], v[100:101], v[114:115]
	v_pk_fma_f32 v[10:11], v[10:11], v[102:103], v[116:117]
	v_pk_fma_f32 v[20:21], v[20:21], v[100:101], v[118:119]
	v_pk_fma_f32 v[22:23], v[22:23], v[102:103], v[120:121]
	v_pk_fma_f32 v[24:25], v[100:101], v[24:25], v[90:91]
	v_pk_fma_f32 v[26:27], v[102:103], v[26:27], v[92:93]
	v_pk_fma_f32 v[28:29], v[100:101], v[28:29], v[96:97]
	v_pk_fma_f32 v[30:31], v[102:103], v[30:31], v[98:99]
	global_store_dwordx4 v[48:49], v[8:11], off offset:-2048 sc0 sc1 nt
	global_store_dwordx4 v[50:51], v[20:23], off offset:-2048 sc0 sc1 nt
	global_store_dwordx4 v[36:37], v[24:27], off offset:-2048 sc0 sc1 nt
	global_store_dwordx4 v[70:71], v[28:31], off offset:-2048 sc0 sc1 nt
	s_nop 1
	v_mov_b32_e32 v90, v200
	v_mov_b32_e32 v91, v201
	v_mov_b32_e32 v92, v202
	v_mov_b32_e32 v93, v203
	s_nop 1
	v_mov_b32_e32 v44, v144
	v_mov_b32_e32 v45, v145
	v_mov_b32_e32 v46, v146
	v_mov_b32_e32 v47, v147
	s_nop 1
	v_mov_b32_e32 v94, v148
	v_mov_b32_e32 v95, v149
	v_mov_b32_e32 v96, v150
	v_mov_b32_e32 v97, v151
	s_nop 1
	v_mov_b32_e32 v98, v152
	v_mov_b32_e32 v99, v153
	v_mov_b32_e32 v100, v154
	v_mov_b32_e32 v101, v155
	s_nop 1
	v_mov_b32_e32 v114, v156
	v_mov_b32_e32 v115, v157
	v_mov_b32_e32 v116, v158
	v_mov_b32_e32 v117, v159
	s_nop 1
	v_mov_b32_e32 v118, v160
	v_mov_b32_e32 v119, v161
	v_mov_b32_e32 v120, v162
	v_mov_b32_e32 v121, v163
	v_pk_fma_f32 v[32:33], v[32:33], v[90:91], v[110:111]
	v_pk_fma_f32 v[34:35], v[34:35], v[92:93], v[112:113]
	v_pk_fma_f32 v[44:45], v[38:39], v[90:91], v[44:45]
	v_pk_fma_f32 v[46:47], v[40:41], v[92:93], v[46:47]
	v_pk_mul_f32 v[38:39], v[80:81], v[84:85] op_sel_hi:[0,1]
	v_pk_mul_f32 v[40:41], v[80:81], v[42:43] op_sel_hi:[0,1]
; __device__ __forceinline__ void ew_post(const bf16* Y, const float* xin, float* xout, const float* gpost, const float* gnext, bf16* H, int gw, int ngw, int lane) {
;     ...
;             for (int q = 0; q < EW_NR; ++q) { xv[q][j] = xv[q][j] + y[q][j] * rstd[q] * g; __builtin_nontemporal_store(xv[q][j], (f32x4*)(xout + (size_t)(m0 + q) * DM) + lane + 64 * j);
;                 s2[q] += (xv[q][j].x * xv[q][j].x + xv[q][j].y * xv[q][j].y) + (xv[q][j].z * xv[q][j].z + xv[q][j].w * xv[q][j].w); } }
;         if (gnext) {
;             float r2[EW_NR];
; #pragma unroll
;             for (int q = 0; q < EW_NR; ++q) r2[q] = rsqrtf(wave_sum(s2[q]) * (1.f / DM) + RMS_EPS);
	s_nop 1
	v_mov_b32_e32 v110, v164
	v_mov_b32_e32 v111, v165
	v_mov_b32_e32 v112, v166
	v_mov_b32_e32 v113, v167
	v_pk_fma_f32 v[40:41], v[40:41], v[90:91], v[94:95]
	v_pk_fma_f32 v[42:43], v[38:39], v[92:93], v[96:97]
	global_store_dwordx4 v[48:49], v[32:35], off offset:-1024 sc0 sc1 nt
	global_store_dwordx4 v[50:51], v[44:47], off offset:-1024 sc0 sc1 nt
	global_store_dwordx4 v[36:37], v[40:43], off offset:-1024 sc0 sc1 nt
	v_pk_mul_f32 v[38:39], v[82:83], v[88:89] op_sel_hi:[0,1]
	v_pk_mul_f32 v[36:37], v[82:83], v[86:87] op_sel_hi:[0,1]
	v_pk_fma_f32 v[36:37], v[90:91], v[36:37], v[98:99]
	v_pk_fma_f32 v[38:39], v[92:93], v[38:39], v[100:101]
	global_store_dwordx4 v[70:71], v[36:39], off offset:-1024 sc0 sc1 nt
	s_nop 1
	v_mov_b32_e32 v88, v204
	v_mov_b32_e32 v89, v205
	v_mov_b32_e32 v90, v206
	v_mov_b32_e32 v91, v207
	s_nop 1
	v_mov_b32_e32 v84, v168
	v_mov_b32_e32 v85, v169
	v_mov_b32_e32 v86, v170
	v_mov_b32_e32 v87, v171
	v_pk_mul_f32 v[82:83], v[82:83], v[56:57] op_sel_hi:[0,1]
	v_pk_mul_f32 v[56:57], v[76:77], v[60:61] op_sel_hi:[0,1]
	v_pk_mul_f32 v[80:81], v[80:81], v[62:63] op_sel_hi:[0,1]
	v_pk_fma_f32 v[60:61], v[58:59], v[88:89], v[114:115]
	v_pk_fma_f32 v[62:63], v[56:57], v[90:91], v[116:117]
	v_pk_fma_f32 v[56:57], v[52:53], v[88:89], v[110:111]
	v_pk_fma_f32 v[58:59], v[54:55], v[90:91], v[112:113]
	v_pk_fma_f32 v[52:53], v[80:81], v[88:89], v[118:119]
	v_pk_fma_f32 v[54:55], v[72:73], v[90:91], v[120:121]
	global_store_dwordx4 v[48:49], v[60:63], off sc0 sc1 nt
	global_store_dwordx4 v[50:51], v[56:59], off sc0 sc1 nt
	global_store_dwordx4 v[70:71], v[52:55], off offset:-4096 sc0 sc1 nt
	v_pk_fma_f32 v[48:49], v[82:83], v[88:89], v[84:85]
	v_pk_fma_f32 v[50:51], v[74:75], v[90:91], v[86:87]
	global_store_dwordx4 v[70:71], v[48:51], off sc0 sc1 nt
	s_cbranch_vccnz .LBB0_190
	v_pk_mul_f32 v[72:73], v[6:7], v[6:7]
	v_pk_mul_f32 v[74:75], v[4:5], v[4:5]
	v_mul_f32_e32 v80, v49, v49
	v_pk_mov_b32 v[76:77], v[74:75], v[72:73] op_sel:[1,0]
	v_mov_b32_e32 v75, v73
	v_pk_add_f32 v[72:73], v[76:77], v[74:75]
	v_pk_mul_f32 v[74:75], v[30:31], v[30:31]
	v_pk_mul_f32 v[76:77], v[28:29], v[28:29]
	v_mul_f32_e32 v81, v50, v50
	v_pk_mov_b32 v[78:79], v[76:77], v[74:75] op_sel:[1,0]
	v_mov_b32_e32 v77, v75
	v_pk_add_f32 v[74:75], v[78:79], v[76:77]
	v_mul_f32_e32 v76, v37, v37
	v_mul_f32_e32 v78, v48, v48
	v_pk_fma_f32 v[76:77], v[36:37], v[36:37], v[76:77] op_sel_hi:[1,1,0]
	v_mul_f32_e32 v82, v51, v51
	v_mov_b32_e32 v77, v78
	v_mul_f32_e32 v78, v39, v39
	v_pk_fma_f32 v[78:79], v[38:39], v[38:39], v[78:79] op_sel_hi:[1,1,0]
	v_pk_add_f32 v[72:73], v[72:73], v[72:73] op_sel:[0,1] op_sel_hi:[1,0]
	v_pk_add_f32 v[74:75], v[74:75], v[74:75] op_sel:[0,1] op_sel_hi:[1,0]
	v_mov_b32_e32 v79, v80
	v_mov_b32_e32 v73, v81
	v_mov_b32_e32 v75, v82
	v_pk_add_f32 v[76:77], v[76:77], v[78:79]
	v_pk_add_f32 v[72:73], v[72:73], v[74:75]
	v_pk_mul_f32 v[74:75], v[16:17], v[16:17]
	v_pk_add_f32 v[76:77], v[76:77], v[72:73]
	v_pk_mul_f32 v[72:73], v[18:19], v[18:19]
	v_mul_f32_e32 v88, v53, v53
	v_pk_mov_b32 v[78:79], v[74:75], v[72:73] op_sel:[1,0]
	v_mov_b32_e32 v75, v73
	v_pk_add_f32 v[72:73], v[78:79], v[74:75]
	v_pk_mul_f32 v[74:75], v[26:27], v[26:27]
	v_pk_mul_f32 v[78:79], v[24:25], v[24:25]
	v_mul_f32_e32 v89, v54, v54
	v_pk_mov_b32 v[80:81], v[78:79], v[74:75] op_sel:[1,0]
	v_mov_b32_e32 v79, v75
	v_pk_add_f32 v[74:75], v[80:81], v[78:79]
	v_mul_f32_e32 v80, v52, v52
	v_pk_add_f32 v[78:79], v[72:73], v[72:73] op_sel:[0,1] op_sel_hi:[1,0]
	v_pk_mul_f32 v[72:73], v[14:15], v[14:15]
	v_mov_b32_e32 v79, v80
	v_pk_mul_f32 v[80:81], v[12:13], v[12:13]
	v_mul_f32_e32 v90, v55, v55
	v_pk_mov_b32 v[82:83], v[80:81], v[72:73] op_sel:[1,0]
	v_mov_b32_e32 v81, v73
	v_pk_add_f32 v[72:73], v[82:83], v[80:81]
	v_pk_mul_f32 v[80:81], v[22:23], v[22:23]
	v_pk_mul_f32 v[82:83], v[20:21], v[20:21]
	v_pk_add_f32 v[72:73], v[72:73], v[72:73] op_sel:[0,1] op_sel_hi:[1,0]
	v_pk_mov_b32 v[84:85], v[82:83], v[80:81] op_sel:[1,0]
	v_mov_b32_e32 v83, v81
	v_pk_add_f32 v[80:81], v[84:85], v[82:83]
	v_mul_f32_e32 v82, v56, v56
	v_mul_f32_e32 v83, v57, v57
	v_pk_add_f32 v[80:81], v[80:81], v[80:81] op_sel:[0,1] op_sel_hi:[1,0]
	v_mov_b32_e32 v73, v82
	v_mov_b32_e32 v81, v83
	v_pk_add_f32 v[72:73], v[72:73], v[80:81]
	v_mul_f32_e32 v80, v45, v45
	v_mul_f32_e32 v82, v47, v47
	v_mul_f32_e32 v84, v58, v58
	v_mul_f32_e32 v85, v59, v59
	v_pk_fma_f32 v[80:81], v[44:45], v[44:45], v[80:81] op_sel_hi:[1,1,0]
	v_pk_fma_f32 v[82:83], v[46:47], v[46:47], v[82:83] op_sel_hi:[1,1,0]
	v_mov_b32_e32 v81, v84
	v_mov_b32_e32 v83, v85
	v_pk_add_f32 v[80:81], v[80:81], v[82:83]
	v_pk_mul_f32 v[82:83], v[0:1], v[0:1]
	v_pk_add_f32 v[72:73], v[72:73], v[80:81]
	v_pk_mul_f32 v[80:81], v[2:3], v[2:3]
	s_nop 0
	v_pk_mov_b32 v[84:85], v[82:83], v[80:81] op_sel:[1,0]
	v_mov_b32_e32 v83, v81
	v_pk_add_f32 v[80:81], v[84:85], v[82:83]
	v_pk_mul_f32 v[82:83], v[10:11], v[10:11]
	v_pk_mul_f32 v[84:85], v[8:9], v[8:9]
	v_pk_add_f32 v[80:81], v[80:81], v[80:81] op_sel:[0,1] op_sel_hi:[1,0]
	v_pk_mov_b32 v[86:87], v[84:85], v[82:83] op_sel:[1,0]
	v_mov_b32_e32 v85, v83
	v_pk_add_f32 v[82:83], v[86:87], v[84:85]
	v_mul_f32_e32 v84, v60, v60
	v_mul_f32_e32 v85, v61, v61
	v_pk_add_f32 v[82:83], v[82:83], v[82:83] op_sel:[0,1] op_sel_hi:[1,0]
	v_mov_b32_e32 v81, v84
	v_mov_b32_e32 v83, v85
	v_pk_add_f32 v[80:81], v[80:81], v[82:83]
	v_mul_f32_e32 v82, v33, v33
	v_mul_f32_e32 v84, v35, v35
	v_mul_f32_e32 v86, v62, v62
	v_mul_f32_e32 v87, v63, v63
	v_pk_fma_f32 v[82:83], v[32:33], v[32:33], v[82:83] op_sel_hi:[1,1,0]
	v_pk_fma_f32 v[84:85], v[34:35], v[34:35], v[84:85] op_sel_hi:[1,1,0]
	v_mov_b32_e32 v83, v86
	v_mov_b32_e32 v85, v87
	v_pk_add_f32 v[82:83], v[82:83], v[84:85]
	v_pk_add_f32 v[84:85], v[74:75], v[74:75] op_sel:[0,1] op_sel_hi:[1,0]
	v_pk_add_f32 v[80:81], v[80:81], v[82:83]
	v_mov_b32_e32 v82, v72
	v_mov_b32_e32 v83, v80
	v_mov_b32_e32 v80, v73
	s_nop 1
	v_mov_b32_e32 v72, v208
	v_mov_b32_e32 v73, v209
	v_mov_b32_e32 v74, v210
	v_mov_b32_e32 v75, v211
	v_pk_add_f32 v[80:81], v[82:83], v[80:81]
	v_mov_b32_e32 v85, v88
	ds_bpermute_b32 v83, v104, v81
	ds_bpermute_b32 v82, v104, v80
	v_pk_add_f32 v[78:79], v[78:79], v[84:85]
	v_mul_f32_e32 v84, v41, v41
	v_mul_f32_e32 v86, v43, v43
	v_pk_fma_f32 v[84:85], v[40:41], v[40:41], v[84:85] op_sel_hi:[1,1,0]
	v_pk_fma_f32 v[86:87], v[42:43], v[42:43], v[86:87] op_sel_hi:[1,1,0]
	v_mov_b32_e32 v85, v89
	v_mov_b32_e32 v87, v90
	v_pk_add_f32 v[84:85], v[84:85], v[86:87]
	s_waitcnt lgkmcnt(0)
; __device__ __forceinline__ float wave_sum(float v) {
; #pragma unroll
;     for (int o = 1; o < 64; o <<= 1) v += __shfl_xor(v, o);
;     return v;
; }
; __device__ __forceinline__ void ew_post(const bf16* Y, const float* xin, float* xout, const float* gpost, const float* gnext, bf16* H, int gw, int ngw, int lane) {
;     ...
;         if (gnext) {
;             float r2[EW_NR];
; #pragma unroll
;             for (int q = 0; q < EW_NR; ++q) r2[q] = rsqrtf(wave_sum(s2[q]) * (1.f / DM) + RMS_EPS);
	v_pk_add_f32 v[80:81], v[80:81], v[82:83]
	v_pk_add_f32 v[78:79], v[78:79], v[84:85]
	v_mov_b32_e32 v84, v76
	v_mov_b32_e32 v85, v78
	v_mov_b32_e32 v78, v77
	ds_bpermute_b32 v83, v105, v81
	ds_bpermute_b32 v82, v105, v80
	v_pk_add_f32 v[76:77], v[84:85], v[78:79]
	ds_bpermute_b32 v79, v104, v77
	ds_bpermute_b32 v78, v104, v76
	s_waitcnt lgkmcnt(2)
	v_pk_add_f32 v[80:81], v[80:81], v[82:83]
	ds_bpermute_b32 v83, v106, v81
	ds_bpermute_b32 v82, v106, v80
	s_waitcnt lgkmcnt(2)
	v_pk_add_f32 v[76:77], v[76:77], v[78:79]
	ds_bpermute_b32 v79, v105, v77
	ds_bpermute_b32 v78, v105, v76
	s_waitcnt lgkmcnt(2)
	v_pk_add_f32 v[80:81], v[80:81], v[82:83]
	ds_bpermute_b32 v83, v107, v81
	ds_bpermute_b32 v82, v107, v80
	s_waitcnt lgkmcnt(2)
	v_pk_add_f32 v[76:77], v[76:77], v[78:79]
	ds_bpermute_b32 v79, v106, v77
	ds_bpermute_b32 v78, v106, v76
	s_waitcnt lgkmcnt(2)
	v_pk_add_f32 v[80:81], v[80:81], v[82:83]
	ds_bpermute_b32 v83, v108, v81
	ds_bpermute_b32 v82, v108, v80
	s_waitcnt lgkmcnt(2)
	v_pk_add_f32 v[76:77], v[76:77], v[78:79]
	ds_bpermute_b32 v79, v107, v77
	ds_bpermute_b32 v78, v107, v76
	s_waitcnt lgkmcnt(2)
	v_pk_add_f32 v[80:81], v[80:81], v[82:83]
	ds_bpermute_b32 v83, v109, v81
	ds_bpermute_b32 v82, v109, v80
	s_waitcnt lgkmcnt(2)
	v_pk_add_f32 v[76:77], v[76:77], v[78:79]
	ds_bpermute_b32 v79, v108, v77
	ds_bpermute_b32 v78, v108, v76
	s_waitcnt lgkmcnt(2)
	v_pk_add_f32 v[80:81], v[80:81], v[82:83]
	v_mov_b64_e32 v[82:83], s[24:25]
	v_pk_fma_f32 v[80:81], v[80:81], s[44:45], v[82:83] op_sel_hi:[1,0,0]
	s_waitcnt lgkmcnt(0)
	v_pk_add_f32 v[76:77], v[76:77], v[78:79]
	v_mul_f32_e32 v84, 0x4b800000, v81
	v_cmp_gt_f32_e32 vcc, s3, v81
	ds_bpermute_b32 v79, v109, v77
	ds_bpermute_b32 v78, v109, v76
	v_cndmask_b32_e32 v81, v81, v84, vcc
	v_rsq_f32_e32 v81, v81
	v_mul_f32_e32 v84, 0x4b800000, v80
	v_cmp_gt_f32_e64 s[4:5], s3, v80
	s_waitcnt lgkmcnt(0)
; __device__ __forceinline__ unsigned pk2(float lo, float hi) { f32v2 v = {lo, hi}; bf16v2 r = __builtin_convertvector(v, bf16v2); return __builtin_bit_cast(unsigned, r); }
; __device__ __forceinline__ void ew_post(const bf16* Y, const float* xin, float* xout, const float* gpost, const float* gnext, bf16* H, int gw, int ngw, int lane) {
;     ...
;             for (int q = 0; q < EW_NR; ++q) r2[q] = rsqrtf(wave_sum(s2[q]) * (1.f / DM) + RMS_EPS);
; #pragma unroll
;             for (int j = 0; j < 4; ++j) { const f32x4 g = *((const f32x4*)gnext + lane + 64 * j);
; #pragma unroll
;                 for (int q = 0; q < EW_NR; ++q) { v2u w; w.x = pk2(xv[q][j].x * r2[q] * g.x, xv[q][j].y * r2[q] * g.y); w.y = pk2(xv[q][j].z * r2[q] * g.z, xv[q][j].w * r2[q] * g.w);
;                     *((v2u*)(H + (size_t)(m0 + q) * DM) + lane + 64 * j) = w; } }
	v_pk_add_f32 v[76:77], v[76:77], v[78:79]
	v_cndmask_b32_e64 v80, v80, v84, s[4:5]
	v_rsq_f32_e32 v84, v80
	v_mul_f32_e32 v80, 0x45800000, v81
	v_pk_fma_f32 v[76:77], v[76:77], s[44:45], v[82:83] op_sel_hi:[1,0,0]
	v_cndmask_b32_e32 v80, v81, v80, vcc
	v_mul_f32_e32 v78, 0x4b800000, v77
	v_cmp_gt_f32_e32 vcc, s3, v77
	v_cmp_gt_f32_e64 s[6:7], s3, v76
	v_mul_f32_e32 v81, 0x45800000, v84
	v_cndmask_b32_e32 v77, v77, v78, vcc
	v_rsq_f32_e32 v77, v77
	v_mul_f32_e32 v78, 0x4b800000, v76
	v_cndmask_b32_e64 v76, v76, v78, s[6:7]
	v_rsq_f32_e32 v79, v76
	v_mul_f32_e32 v78, 0x45800000, v77
	v_pk_mul_f32 v[0:1], v[0:1], v[80:81] op_sel_hi:[1,0]
	v_pk_mul_f32 v[2:3], v[2:3], v[80:81] op_sel_hi:[1,0]
	v_cndmask_b32_e64 v76, v84, v81, s[4:5]
	v_cndmask_b32_e32 v78, v77, v78, vcc
	v_pk_mul_f32 v[0:1], v[0:1], v[72:73]
	v_pk_mul_f32 v[2:3], v[2:3], v[74:75]
	v_add_co_u32_e32 v84, vcc, s22, v68
	v_mul_f32_e32 v77, 0x45800000, v79
	v_cvt_pk_bf16_f32 v0, v0, v1
	v_cvt_pk_bf16_f32 v1, v2, v3
	v_addc_co_u32_e32 v85, vcc, -1, v69, vcc
	global_store_dwordx2 v[84:85], v[0:1], off offset:-3584
	v_pk_mul_f32 v[0:1], v[12:13], v[76:77] op_sel_hi:[1,0]
	v_pk_mul_f32 v[2:3], v[14:15], v[76:77] op_sel_hi:[1,0]
	v_pk_mul_f32 v[0:1], v[0:1], v[72:73]
	v_pk_mul_f32 v[2:3], v[2:3], v[74:75]
	v_cvt_pk_bf16_f32 v0, v0, v1
	v_cvt_pk_bf16_f32 v1, v2, v3
	global_store_dwordx2 v[84:85], v[0:1], off offset:-1536
	v_pk_mul_f32 v[0:1], v[16:17], v[78:79] op_sel_hi:[1,0]
	v_pk_mul_f32 v[2:3], v[18:19], v[78:79] op_sel_hi:[1,0]
	v_pk_mul_f32 v[0:1], v[72:73], v[0:1]
	v_pk_mul_f32 v[2:3], v[74:75], v[2:3]
	v_add_co_u32_e32 v12, vcc, s23, v68
	v_cndmask_b32_e64 v82, v79, v77, s[6:7]
	v_cvt_pk_bf16_f32 v0, v0, v1
	v_cvt_pk_bf16_f32 v1, v2, v3
	v_addc_co_u32_e32 v13, vcc, -1, v69, vcc
	global_store_dwordx2 v[12:13], v[0:1], off offset:-3584
	v_pk_mul_f32 v[0:1], v[4:5], v[82:83] op_sel_hi:[1,0]
	v_pk_mul_f32 v[2:3], v[6:7], v[82:83] op_sel_hi:[1,0]
	v_pk_mul_f32 v[0:1], v[72:73], v[0:1]
	v_pk_mul_f32 v[2:3], v[74:75], v[2:3]
	v_cvt_pk_bf16_f32 v0, v0, v1
	v_cvt_pk_bf16_f32 v1, v2, v3
	global_store_dwordx2 v[12:13], v[0:1], off offset:-1536
	s_nop 1
	v_mov_b32_e32 v0, v212
	v_mov_b32_e32 v1, v213
	v_mov_b32_e32 v2, v214
	v_mov_b32_e32 v3, v215
	v_pk_mul_f32 v[4:5], v[8:9], v[80:81] op_sel_hi:[1,0]
	v_pk_mul_f32 v[6:7], v[10:11], v[80:81] op_sel_hi:[1,0]
	v_pk_mul_f32 v[8:9], v[56:57], v[76:77] op_sel_hi:[1,0]
	v_pk_mul_f32 v[10:11], v[58:59], v[76:77] op_sel_hi:[1,0]
	v_pk_mul_f32 v[14:15], v[52:53], v[78:79] op_sel_hi:[1,0]
	v_pk_mul_f32 v[16:17], v[54:55], v[78:79] op_sel_hi:[1,0]
	v_pk_mul_f32 v[18:19], v[48:49], v[82:83] op_sel_hi:[1,0]
	v_pk_mul_f32 v[4:5], v[4:5], v[0:1]
	v_pk_mul_f32 v[6:7], v[6:7], v[2:3]
	v_cvt_pk_bf16_f32 v4, v4, v5
	v_cvt_pk_bf16_f32 v5, v6, v7
	global_store_dwordx2 v[84:85], v[4:5], off offset:-3072
	v_pk_mul_f32 v[4:5], v[20:21], v[76:77] op_sel_hi:[1,0]
	v_pk_mul_f32 v[6:7], v[22:23], v[76:77] op_sel_hi:[1,0]
	v_pk_mul_f32 v[4:5], v[4:5], v[0:1]
	v_pk_mul_f32 v[6:7], v[6:7], v[2:3]
	v_cvt_pk_bf16_f32 v4, v4, v5
	v_cvt_pk_bf16_f32 v5, v6, v7
	global_store_dwordx2 v[84:85], v[4:5], off offset:-1024
	v_pk_mul_f32 v[4:5], v[24:25], v[78:79] op_sel_hi:[1,0]
	v_pk_mul_f32 v[6:7], v[26:27], v[78:79] op_sel_hi:[1,0]
	v_pk_mul_f32 v[4:5], v[4:5], v[0:1]
	v_pk_mul_f32 v[6:7], v[6:7], v[2:3]
	v_cvt_pk_bf16_f32 v4, v4, v5
	v_cvt_pk_bf16_f32 v5, v6, v7
	global_store_dwordx2 v[12:13], v[4:5], off offset:-3072
	v_pk_mul_f32 v[4:5], v[28:29], v[82:83] op_sel_hi:[1,0]
	v_pk_mul_f32 v[6:7], v[34:35], v[80:81] op_sel_hi:[1,0]
	v_pk_mul_f32 v[0:1], v[0:1], v[4:5]
	v_pk_mul_f32 v[4:5], v[30:31], v[82:83] op_sel_hi:[1,0]
	v_cvt_pk_bf16_f32 v0, v0, v1
	v_pk_mul_f32 v[2:3], v[2:3], v[4:5]
	v_pk_mul_f32 v[4:5], v[32:33], v[80:81] op_sel_hi:[1,0]
	v_cvt_pk_bf16_f32 v1, v2, v3
	global_store_dwordx2 v[12:13], v[0:1], off offset:-1024
	s_nop 1
	v_mov_b32_e32 v0, v216
	v_mov_b32_e32 v1, v217
	v_mov_b32_e32 v2, v218
	v_mov_b32_e32 v3, v219
	v_pk_mul_f32 v[20:21], v[50:51], v[82:83] op_sel_hi:[1,0]
	v_pk_mul_f32 v[4:5], v[4:5], v[0:1]
	v_pk_mul_f32 v[6:7], v[6:7], v[2:3]
	v_cvt_pk_bf16_f32 v4, v4, v5
	v_cvt_pk_bf16_f32 v5, v6, v7
	global_store_dwordx2 v[84:85], v[4:5], off offset:-2560
	v_pk_mul_f32 v[4:5], v[44:45], v[76:77] op_sel_hi:[1,0]
	v_pk_mul_f32 v[6:7], v[46:47], v[76:77] op_sel_hi:[1,0]
	v_pk_mul_f32 v[4:5], v[4:5], v[0:1]
	v_pk_mul_f32 v[6:7], v[6:7], v[2:3]
	v_cvt_pk_bf16_f32 v4, v4, v5
	v_cvt_pk_bf16_f32 v5, v6, v7
	global_store_dwordx2 v[84:85], v[4:5], off offset:-512
	v_pk_mul_f32 v[4:5], v[40:41], v[78:79] op_sel_hi:[1,0]
	v_pk_mul_f32 v[6:7], v[42:43], v[78:79] op_sel_hi:[1,0]
	v_pk_mul_f32 v[4:5], v[4:5], v[0:1]
	v_pk_mul_f32 v[6:7], v[6:7], v[2:3]
	v_cvt_pk_bf16_f32 v4, v4, v5
	v_cvt_pk_bf16_f32 v5, v6, v7
	global_store_dwordx2 v[12:13], v[4:5], off offset:-2560
	v_pk_mul_f32 v[4:5], v[36:37], v[82:83] op_sel_hi:[1,0]
	v_pk_mul_f32 v[6:7], v[62:63], v[80:81] op_sel_hi:[1,0]
	v_pk_mul_f32 v[0:1], v[4:5], v[0:1]
	v_pk_mul_f32 v[4:5], v[38:39], v[82:83] op_sel_hi:[1,0]
	v_cvt_pk_bf16_f32 v0, v0, v1
	v_pk_mul_f32 v[2:3], v[4:5], v[2:3]
	v_pk_mul_f32 v[4:5], v[60:61], v[80:81] op_sel_hi:[1,0]
	v_cvt_pk_bf16_f32 v1, v2, v3
	global_store_dwordx2 v[12:13], v[0:1], off offset:-512
	s_nop 1
	v_mov_b32_e32 v0, v220
	v_mov_b32_e32 v1, v221
	v_mov_b32_e32 v2, v222
	v_mov_b32_e32 v3, v223
	v_pk_mul_f32 v[4:5], v[4:5], v[0:1]
	v_pk_mul_f32 v[6:7], v[6:7], v[2:3]
	v_pk_mul_f32 v[8:9], v[8:9], v[0:1]
	v_pk_mul_f32 v[10:11], v[10:11], v[2:3]
	v_pk_mul_f32 v[14:15], v[14:15], v[0:1]
	v_pk_mul_f32 v[16:17], v[16:17], v[2:3]
	v_pk_mul_f32 v[0:1], v[18:19], v[0:1]
	v_pk_mul_f32 v[2:3], v[20:21], v[2:3]
	v_cvt_pk_bf16_f32 v4, v4, v5
	v_cvt_pk_bf16_f32 v5, v6, v7
	v_cvt_pk_bf16_f32 v6, v8, v9
	v_cvt_pk_bf16_f32 v7, v10, v11
	v_cvt_pk_bf16_f32 v8, v14, v15
	v_cvt_pk_bf16_f32 v9, v16, v17
	v_cvt_pk_bf16_f32 v0, v0, v1
	v_cvt_pk_bf16_f32 v1, v2, v3
	global_store_dwordx2 v[84:85], v[4:5], off offset:-2048
	global_store_dwordx2 v[12:13], v[6:7], off offset:-4096
	global_store_dwordx2 v[12:13], v[8:9], off offset:-2048
	global_store_dwordx2 v[12:13], v[0:1], off
	s_branch .LBB0_190

; __device__ __forceinline__ void ew_post(const bf16* Y, const float* xin, float* xout, const float* gpost, const float* gnext, bf16* H, int gw, int ngw, int lane) {
;     for (int m0 = EW_NR * gw; m0 < NTOK; m0 += EW_NR * ngw) {
;         f32x4 y[EW_NR][4], xv[EW_NR][4]; float s[EW_NR];
; #pragma unroll
;         for (int q = 0; q < EW_NR; ++q) { const v2u* yr = (const v2u*)(Y + (size_t)(m0 + q) * DM) + lane; const f32x4* xr = (const f32x4*)(xin + (size_t)(m0 + q) * DM) + lane;
; #pragma unroll
;             for (int j = 0; j < 4; ++j) { const v2u w = __builtin_nontemporal_load(yr + 64 * j); y[q][j] = (f32x4){bf_lo(w.x), bf_hi(w.x), bf_lo(w.y), bf_hi(w.y)}; xv[q][j] = __builtin_nontemporal_load(xr + 64 * j); } }
; #pragma unroll
;         for (int q = 0; q < EW_NR; ++q) { s[q] = 0.f;
; #pragma unroll
;             for (int j = 0; j < 4; ++j) s[q] += (y[q][j].x * y[q][j].x + y[q][j].y * y[q][j].y) + (y[q][j].z * y[q][j].z + y[q][j].w * y[q][j].w); }
.LBB0_209:
	v_add_co_u32_e32 v8, vcc, 0xfffff000, v72
	global_load_dwordx2 v[38:39], v[72:73], off offset:-4096 nt
	global_load_dwordx2 v[40:41], v[72:73], off offset:-2048 nt
	v_addc_co_u32_e32 v9, vcc, -1, v73, vcc
	global_load_dwordx2 v[42:43], v[72:73], off nt
	global_load_dwordx2 v[48:49], v[8:9], off offset:-2048 nt
	global_load_dwordx2 v[50:51], v[8:9], off offset:-3584 nt
	global_load_dwordx2 v[52:53], v[8:9], off offset:-3072 nt
	global_load_dwordx2 v[54:55], v[8:9], off offset:-2560 nt
	v_lshl_add_u64 v[10:11], s[12:13], 0, v[178:179]
	global_load_dwordx2 v[96:97], v[72:73], off offset:-3584 nt
	global_load_dwordx2 v[106:107], v[72:73], off offset:-3072 nt
	global_load_dwordx2 v[98:99], v[72:73], off offset:-2560 nt
	global_load_dwordx2 v[108:109], v[72:73], off offset:-1536 nt
	global_load_dwordx2 v[66:67], v[72:73], off offset:-1024 nt
	global_load_dwordx2 v[46:47], v[72:73], off offset:-512 nt
	global_load_dwordx2 v[90:91], v[8:9], off offset:-1536 nt
	global_load_dwordx4 v[20:23], v[10:11], off nt
	global_load_dwordx4 v[12:15], v[10:11], off offset:1024 nt
	global_load_dwordx4 v[4:7], v[10:11], off offset:2048 nt
	global_load_dwordx4 v[0:3], v[10:11], off offset:3072 nt
	global_load_dwordx2 v[92:93], v[8:9], off offset:-1024 nt
	global_load_dwordx2 v[104:105], v[8:9], off offset:-512 nt
	v_add_co_u32_e64 v36, s[4:5], s24, v10
	v_add_co_u32_e32 v44, vcc, s22, v10
	s_nop 0
	v_addc_co_u32_e64 v37, s[4:5], 0, v11, s[4:5]
	s_mov_b64 s[4:5], vcc
	v_add_co_u32_e32 v64, vcc, s23, v10
	v_addc_co_u32_e64 v45, s[4:5], 0, v11, s[4:5]
	global_load_dwordx4 v[28:31], v[36:37], off nt
	v_addc_co_u32_e32 v65, vcc, 0, v11, vcc
	global_load_dwordx4 v[16:19], v[44:45], off offset:1024 nt
	global_load_dwordx4 v[8:11], v[44:45], off offset:2048 nt
	global_load_dwordx4 v[24:27], v[64:65], off offset:-4096 nt
	global_load_dwordx4 v[32:35], v[64:65], off nt
	s_nop 1
	v_mov_b32_e32 v136, v156
	v_mov_b32_e32 v137, v157
	v_mov_b32_e32 v138, v158
	v_mov_b32_e32 v139, v159
	v_mov_b64_e32 v[148:149], s[26:27]
	global_load_dwordx4 v[192:195], v[44:45], off offset:3072 nt
	global_load_dwordx4 v[196:199], v[64:65], off offset:1024 nt
	global_load_dwordx4 v[200:203], v[64:65], off offset:2048 nt
	global_load_dwordx4 v[204:207], v[64:65], off offset:3072 nt
	global_load_dwordx4 v[208:211], v[36:37], off offset:1024 nt
	global_load_dwordx4 v[212:215], v[36:37], off offset:2048 nt
	global_load_dwordx4 v[216:219], v[36:37], off offset:3072 nt
	s_waitcnt vmcnt(0)
	v_and_b32_e32 v121, 0xffff0000, v97
	v_and_b32_e32 v119, 0xffff0000, v96
	v_lshlrev_b32_e32 v120, 16, v97
	v_lshlrev_b32_e32 v118, 16, v96
	v_lshlrev_b32_e32 v59, 16, v38
	v_lshlrev_b32_e32 v77, 16, v40
	v_lshlrev_b32_e32 v87, 16, v48
	v_and_b32_e32 v101, 0xffff0000, v50
	v_and_b32_e32 v103, 0xffff0000, v51
	v_and_b32_e32 v75, 0xffff0000, v40
	v_lshlrev_b32_e32 v78, 16, v41
	v_and_b32_e32 v79, 0xffff0000, v41
	v_lshlrev_b32_e32 v83, 16, v42
	v_and_b32_e32 v81, 0xffff0000, v42
	v_lshlrev_b32_e32 v84, 16, v43
	v_and_b32_e32 v85, 0xffff0000, v43
	v_and_b32_e32 v63, 0xffff0000, v48
	v_lshlrev_b32_e32 v88, 16, v49
	v_and_b32_e32 v89, 0xffff0000, v49
	v_lshlrev_b32_e32 v100, 16, v50
	v_lshlrev_b32_e32 v102, 16, v51
	v_and_b32_e32 v41, 0xffff0000, v53
	v_and_b32_e32 v40, 0xffff0000, v52
	v_lshlrev_b32_e32 v48, 16, v54
	v_and_b32_e32 v49, 0xffff0000, v54
	v_mul_f32_e32 v42, v103, v103
	v_mul_f32_e32 v54, v101, v101
	v_mov_b32_e32 v43, v87
	v_and_b32_e32 v57, 0xffff0000, v38
	v_lshlrev_b32_e32 v60, 16, v39
	v_and_b32_e32 v61, 0xffff0000, v39
	v_lshlrev_b32_e32 v39, 16, v53
	v_lshlrev_b32_e32 v38, 16, v52
	v_lshlrev_b32_e32 v50, 16, v55
	v_and_b32_e32 v51, 0xffff0000, v55
	v_pk_mul_f32 v[52:53], v[40:41], v[40:41]
	v_pk_fma_f32 v[94:95], v[102:103], v[102:103], v[42:43] op_sel_hi:[1,1,0]
	v_pk_fma_f32 v[54:55], v[100:101], v[100:101], v[54:55] op_sel_hi:[1,1,0]
	v_pk_fma_f32 v[52:53], v[38:39], v[38:39], v[52:53]
	v_mov_b32_e32 v86, v54
	v_mov_b32_e32 v42, v94
	v_mul_f32_e32 v56, v63, v63
	v_pk_add_f32 v[54:55], v[54:55], v[94:95]
	v_pk_add_f32 v[52:53], v[52:53], v[52:53] op_sel:[0,1] op_sel_hi:[1,0]
	v_pk_mul_f32 v[42:43], v[86:87], v[42:43]
	v_mov_b32_e32 v53, v56
	v_mov_b32_e32 v55, v43
	v_pk_add_f32 v[42:43], v[54:55], v[52:53]
	v_mul_f32_e32 v52, v49, v49
	v_mul_f32_e32 v54, v51, v51
	v_mul_f32_e32 v58, v88, v88
	v_mul_f32_e32 v62, v89, v89
	v_pk_fma_f32 v[52:53], v[48:49], v[48:49], v[52:53] op_sel_hi:[1,1,0]
	v_pk_fma_f32 v[54:55], v[50:51], v[50:51], v[54:55] op_sel_hi:[1,1,0]
	v_mov_b32_e32 v53, v58
	v_mov_b32_e32 v55, v62
	v_pk_add_f32 v[52:53], v[52:53], v[54:55]
	v_and_b32_e32 v113, 0xffff0000, v91
	v_pk_add_f32 v[52:53], v[42:43], v[52:53]
	v_and_b32_e32 v111, 0xffff0000, v90
	v_lshlrev_b32_e32 v112, 16, v91
	v_mul_f32_e32 v42, v113, v113
	v_and_b32_e32 v95, 0xffff0000, v93
	v_and_b32_e32 v94, 0xffff0000, v92
	v_lshlrev_b32_e32 v110, 16, v90
	v_pk_fma_f32 v[54:55], v[112:113], v[112:113], v[42:43] op_sel_hi:[1,1,0]
	v_lshlrev_b32_e32 v43, 16, v93
	v_lshlrev_b32_e32 v42, 16, v92
	v_pk_mul_f32 v[90:91], v[94:95], v[94:95]
	v_mul_f32_e32 v56, v111, v111
	v_pk_fma_f32 v[114:115], v[42:43], v[42:43], v[90:91]
	v_lshlrev_b32_e32 v90, 16, v104
	v_and_b32_e32 v91, 0xffff0000, v104
	v_lshlrev_b32_e32 v92, 16, v105
	v_and_b32_e32 v93, 0xffff0000, v105
	v_pk_fma_f32 v[104:105], v[110:111], v[110:111], v[56:57] op_sel_hi:[1,1,0]
	v_mov_b32_e32 v116, v54
	v_mov_b32_e32 v58, v104
	v_mov_b32_e32 v117, v59
	v_pk_add_f32 v[54:55], v[104:105], v[54:55]
	v_pk_mul_f32 v[104:105], v[58:59], v[116:117]
	v_mul_f32_e32 v62, v57, v57
	v_mov_b32_e32 v55, v105
	v_pk_add_f32 v[104:105], v[114:115], v[114:115] op_sel:[0,1] op_sel_hi:[1,0]
	v_mul_f32_e32 v56, v91, v91
	v_mov_b32_e32 v105, v62
	v_pk_add_f32 v[54:55], v[54:55], v[104:105]
	v_pk_fma_f32 v[104:105], v[90:91], v[90:91], v[56:57] op_sel_hi:[1,1,0]
	v_mul_f32_e32 v56, v93, v93
	v_mul_f32_e32 v74, v60, v60
	v_mul_f32_e32 v76, v61, v61
	v_pk_fma_f32 v[114:115], v[92:93], v[92:93], v[56:57] op_sel_hi:[1,1,0]
	v_mov_b32_e32 v105, v74
	v_mov_b32_e32 v115, v76
	v_pk_add_f32 v[104:105], v[104:105], v[114:115]
	v_mov_b32_e32 v143, v52
	v_pk_add_f32 v[54:55], v[54:55], v[104:105]
	v_mul_f32_e32 v56, v121, v121
	v_mov_b32_e32 v142, v54
	v_mov_b32_e32 v52, v55
	v_pk_add_f32 v[52:53], v[142:143], v[52:53]
	ds_bpermute_b32 v55, v130, v53
	ds_bpermute_b32 v54, v130, v52
	v_pk_fma_f32 v[114:115], v[120:121], v[120:121], v[56:57] op_sel_hi:[1,1,0]
	v_lshlrev_b32_e32 v105, 16, v107
	v_lshlrev_b32_e32 v104, 16, v106
	v_and_b32_e32 v107, 0xffff0000, v107
	v_and_b32_e32 v106, 0xffff0000, v106
	v_mul_f32_e32 v56, v119, v119
	v_pk_mul_f32 v[96:97], v[106:107], v[106:107]
	v_pk_fma_f32 v[122:123], v[118:119], v[118:119], v[56:57] op_sel_hi:[1,1,0]
	s_waitcnt lgkmcnt(0)
; __device__ __forceinline__ void ew_post(const bf16* Y, const float* xin, float* xout, const float* gpost, const float* gnext, bf16* H, int gw, int ngw, int lane) {
;     ...
;         for (int q = 0; q < EW_NR; ++q) { s[q] = 0.f;
; #pragma unroll
;             for (int j = 0; j < 4; ++j) s[q] += (y[q][j].x * y[q][j].x + y[q][j].y * y[q][j].y) + (y[q][j].z * y[q][j].z + y[q][j].w * y[q][j].w); }
;         float rstd[EW_NR], s2[EW_NR];
; #pragma unroll
;         for (int q = 0; q < EW_NR; ++q) { rstd[q] = rsqrtf(wave_sum(s[q]) * (1.f / DM) + RMS_EPS); s2[q] = 0.f; }
; #pragma unroll
;         for (int j = 0; j < 4; ++j) { const f32x4 g = *((const f32x4*)gpost + lane + 64 * j);
; #pragma unroll
;             for (int q = 0; q < EW_NR; ++q) { xv[q][j] = xv[q][j] + y[q][j] * rstd[q] * g; __builtin_nontemporal_store(xv[q][j], (f32x4*)(xout + (size_t)(m0 + q) * DM) + lane + 64 * j);
;                 s2[q] += (xv[q][j].x * xv[q][j].x + xv[q][j].y * xv[q][j].y) + (xv[q][j].z * xv[q][j].z + xv[q][j].w * xv[q][j].w); } }
	v_pk_add_f32 v[52:53], v[52:53], v[54:55]
	v_pk_fma_f32 v[116:117], v[104:105], v[104:105], v[96:97]
	v_mov_b32_e32 v76, v122
	v_mov_b32_e32 v124, v114
	v_mov_b32_e32 v125, v77
	ds_bpermute_b32 v55, v131, v53
	ds_bpermute_b32 v54, v131, v52
	v_and_b32_e32 v97, 0xffff0000, v98
	v_mul_f32_e32 v58, v75, v75
	v_pk_add_f32 v[114:115], v[122:123], v[114:115]
	v_pk_mul_f32 v[122:123], v[76:77], v[124:125]
	v_pk_add_f32 v[116:117], v[116:117], v[116:117] op_sel:[0,1] op_sel_hi:[1,0]
	v_lshlrev_b32_e32 v96, 16, v98
	v_lshlrev_b32_e32 v98, 16, v99
	v_and_b32_e32 v99, 0xffff0000, v99
	v_mov_b32_e32 v115, v123
	v_mov_b32_e32 v117, v58
	v_mul_f32_e32 v56, v97, v97
	v_pk_add_f32 v[114:115], v[114:115], v[116:117]
	v_pk_fma_f32 v[116:117], v[96:97], v[96:97], v[56:57] op_sel_hi:[1,1,0]
	v_mul_f32_e32 v56, v99, v99
	v_mul_f32_e32 v62, v78, v78
	v_mul_f32_e32 v74, v79, v79
	v_pk_fma_f32 v[122:123], v[98:99], v[98:99], v[56:57] op_sel_hi:[1,1,0]
	v_mov_b32_e32 v117, v62
	v_mov_b32_e32 v123, v74
	s_waitcnt lgkmcnt(0)
	v_pk_add_f32 v[52:53], v[52:53], v[54:55]
	v_pk_add_f32 v[116:117], v[116:117], v[122:123]
	v_and_b32_e32 v123, 0xffff0000, v108
	v_and_b32_e32 v125, 0xffff0000, v109
	ds_bpermute_b32 v55, v132, v53
	ds_bpermute_b32 v54, v132, v52
	v_pk_add_f32 v[128:129], v[114:115], v[116:117]
	v_lshlrev_b32_e32 v122, 16, v108
	v_lshlrev_b32_e32 v124, 16, v109
	v_mul_f32_e32 v56, v125, v125
	v_and_b32_e32 v117, 0xffff0000, v67
	v_and_b32_e32 v116, 0xffff0000, v66
	v_lshlrev_b32_e32 v108, 16, v46
	v_and_b32_e32 v109, 0xffff0000, v46
	v_mul_f32_e32 v46, v123, v123
	v_pk_fma_f32 v[140:141], v[124:125], v[124:125], v[56:57] op_sel_hi:[1,1,0]
	v_lshlrev_b32_e32 v115, 16, v67
	v_lshlrev_b32_e32 v114, 16, v66
	v_pk_mul_f32 v[66:67], v[116:117], v[116:117]
	v_lshlrev_b32_e32 v126, 16, v47
	v_and_b32_e32 v127, 0xffff0000, v47
	v_pk_fma_f32 v[46:47], v[122:123], v[122:123], v[46:47] op_sel_hi:[1,1,0]
	v_pk_fma_f32 v[66:67], v[114:115], v[114:115], v[66:67]
	v_mov_b32_e32 v82, v46
	v_mov_b32_e32 v142, v140
	v_mov_b32_e32 v143, v83
	v_mul_f32_e32 v56, v81, v81
	v_pk_add_f32 v[46:47], v[46:47], v[140:141]
	v_pk_mul_f32 v[140:141], v[82:83], v[142:143]
	v_pk_add_f32 v[66:67], v[66:67], v[66:67] op_sel:[0,1] op_sel_hi:[1,0]
	v_mov_b32_e32 v47, v141
	v_mov_b32_e32 v67, v56
	v_mul_f32_e32 v56, v109, v109
	s_waitcnt lgkmcnt(0)
	v_pk_add_f32 v[52:53], v[52:53], v[54:55]
	v_pk_add_f32 v[46:47], v[46:47], v[66:67]
	v_pk_fma_f32 v[66:67], v[108:109], v[108:109], v[56:57] op_sel_hi:[1,1,0]
	v_mul_f32_e32 v56, v127, v127
	ds_bpermute_b32 v55, v133, v53
	ds_bpermute_b32 v54, v133, v52
	v_mul_f32_e32 v58, v84, v84
	v_mul_f32_e32 v62, v85, v85
	v_pk_fma_f32 v[140:141], v[126:127], v[126:127], v[56:57] op_sel_hi:[1,1,0]
	v_mov_b32_e32 v67, v58
	v_mov_b32_e32 v141, v62
	v_pk_add_f32 v[66:67], v[66:67], v[140:141]
	v_mov_b32_e32 v74, v77
	v_pk_add_f32 v[46:47], v[46:47], v[66:67]
	s_waitcnt lgkmcnt(0)
	v_pk_add_f32 v[66:67], v[52:53], v[54:55]
	v_mov_b32_e32 v52, v46
	v_mov_b32_e32 v53, v128
	v_mov_b32_e32 v128, v47
	ds_bpermute_b32 v141, v134, v67
	ds_bpermute_b32 v140, v134, v66
	v_pk_add_f32 v[46:47], v[52:53], v[128:129]
	ds_bpermute_b32 v129, v130, v47
	ds_bpermute_b32 v128, v130, v46
	s_nop 1
	v_mov_b32_e32 v52, v192
	v_mov_b32_e32 v53, v193
	v_mov_b32_e32 v54, v194
	v_mov_b32_e32 v55, v195
	s_waitcnt lgkmcnt(2)
	v_pk_add_f32 v[44:45], v[66:67], v[140:141]
	ds_bpermute_b32 v67, v135, v45
	ds_bpermute_b32 v66, v135, v44
	s_waitcnt lgkmcnt(2)
	v_pk_add_f32 v[46:47], v[46:47], v[128:129]
	ds_bpermute_b32 v129, v131, v47
	ds_bpermute_b32 v128, v131, v46
	s_nop 1
	v_mov_b32_e32 v140, v196
	v_mov_b32_e32 v141, v197
	v_mov_b32_e32 v142, v198
	v_mov_b32_e32 v143, v199
	s_waitcnt lgkmcnt(2)
	v_pk_add_f32 v[44:45], v[44:45], v[66:67]
	v_mov_b32_e32 v80, v83
	v_pk_fma_f32 v[150:151], v[44:45], s[44:45], v[148:149] op_sel_hi:[1,0,0]
	s_waitcnt lgkmcnt(0)
	v_pk_add_f32 v[44:45], v[46:47], v[128:129]
	ds_bpermute_b32 v47, v132, v45
	ds_bpermute_b32 v46, v132, v44
	v_mul_f32_e32 v56, 0x4b800000, v151
	v_cmp_gt_f32_e32 vcc, s3, v151
	s_waitcnt lgkmcnt(0)
	v_pk_add_f32 v[128:129], v[44:45], v[46:47]
	ds_bpermute_b32 v145, v133, v129
	ds_bpermute_b32 v144, v133, v128
	v_cndmask_b32_e32 v56, v151, v56, vcc
	v_rsq_f32_e32 v56, v56
	s_nop 1
	v_mov_b32_e32 v44, v200
	v_mov_b32_e32 v45, v201
	v_mov_b32_e32 v46, v202
	v_mov_b32_e32 v47, v203
	s_nop 0
	s_nop 1
	v_mov_b32_e32 v64, v204
	v_mov_b32_e32 v65, v205
	v_mov_b32_e32 v66, v206
	v_mov_b32_e32 v67, v207
	s_waitcnt lgkmcnt(0)
	v_pk_add_f32 v[128:129], v[128:129], v[144:145]
	ds_bpermute_b32 v153, v134, v129
	ds_bpermute_b32 v152, v134, v128
	v_mul_f32_e32 v58, 0x45800000, v56
	v_cndmask_b32_e32 v56, v56, v58, vcc
	v_mul_f32_e32 v58, 0x4b800000, v150
	v_cmp_gt_f32_e32 vcc, s3, v150
	s_waitcnt lgkmcnt(0)
	v_pk_add_f32 v[128:129], v[128:129], v[152:153]
	ds_bpermute_b32 v153, v135, v129
	ds_bpermute_b32 v152, v135, v128
	v_cndmask_b32_e32 v58, v150, v58, vcc
	v_rsq_f32_e32 v58, v58
	v_pk_mul_f32 v[100:101], v[56:57], v[100:101] op_sel_hi:[0,1]
	v_pk_mul_f32 v[102:103], v[56:57], v[102:103] op_sel_hi:[0,1]
	s_waitcnt lgkmcnt(0)
; __device__ __forceinline__ void ew_post(const bf16* Y, const float* xin, float* xout, const float* gpost, const float* gnext, bf16* H, int gw, int ngw, int lane) {
;     ...
;         for (int q = 0; q < EW_NR; ++q) { rstd[q] = rsqrtf(wave_sum(s[q]) * (1.f / DM) + RMS_EPS); s2[q] = 0.f; }
; #pragma unroll
;         for (int j = 0; j < 4; ++j) { const f32x4 g = *((const f32x4*)gpost + lane + 64 * j);
; #pragma unroll
;             for (int q = 0; q < EW_NR; ++q) { xv[q][j] = xv[q][j] + y[q][j] * rstd[q] * g; __builtin_nontemporal_store(xv[q][j], (f32x4*)(xout + (size_t)(m0 + q) * DM) + lane + 64 * j);
;                 s2[q] += (xv[q][j].x * xv[q][j].x + xv[q][j].y * xv[q][j].y) + (xv[q][j].z * xv[q][j].z + xv[q][j].w * xv[q][j].w); } }
;         if (gnext) {
	v_pk_add_f32 v[128:129], v[128:129], v[152:153]
	v_pk_fma_f32 v[22:23], v[102:103], v[138:139], v[22:23]
	v_pk_fma_f32 v[128:129], v[128:129], s[44:45], v[148:149] op_sel_hi:[1,0,0]
	v_pk_fma_f32 v[20:21], v[100:101], v[136:137], v[20:21]
	v_mul_f32_e32 v62, 0x4b800000, v129
	v_cmp_gt_f32_e64 s[4:5], s3, v129
	s_nop 1
	v_mov_b32_e32 v100, v208
	v_mov_b32_e32 v101, v209
	v_mov_b32_e32 v102, v210
	v_mov_b32_e32 v103, v211
	s_nop 1
	v_mov_b32_e32 v144, v212
	v_mov_b32_e32 v145, v213
	v_mov_b32_e32 v146, v214
	v_mov_b32_e32 v147, v215
	v_cndmask_b32_e64 v62, v129, v62, s[4:5]
	v_rsq_f32_e32 v62, v62
	s_nop 1
	v_mov_b32_e32 v148, v216
	v_mov_b32_e32 v149, v217
	v_mov_b32_e32 v150, v218
	v_mov_b32_e32 v151, v219
	v_mul_f32_e32 v36, 0x45800000, v58
	v_cndmask_b32_e32 v58, v58, v36, vcc
	v_mul_f32_e32 v36, 0x45800000, v62
	v_cndmask_b32_e64 v76, v62, v36, s[4:5]
	v_mul_f32_e32 v36, 0x4b800000, v128
	v_cmp_gt_f32_e32 vcc, s3, v128
	v_pk_mul_f32 v[50:51], v[56:57], v[50:51] op_sel_hi:[0,1]
	v_pk_mul_f32 v[48:49], v[56:57], v[48:49] op_sel_hi:[0,1]
	v_cndmask_b32_e32 v36, v128, v36, vcc
	v_rsq_f32_e32 v62, v36
	v_pk_mul_f32 v[36:37], v[58:59], v[110:111] op_sel_hi:[0,1]
	v_pk_fma_f32 v[24:25], v[36:37], v[136:137], v[24:25]
	v_lshl_add_u64 v[128:129], s[10:11], 0, v[178:179]
	v_mul_f32_e32 v36, 0x45800000, v62
	v_pk_mul_f32 v[110:111], v[58:59], v[112:113] op_sel_hi:[0,1]
	v_cndmask_b32_e32 v82, v62, v36, vcc
	v_pk_mul_f32 v[36:37], v[76:77], v[118:119] op_sel_hi:[0,1]
	v_add_co_u32_e32 v118, vcc, s23, v128
	v_pk_fma_f32 v[26:27], v[110:111], v[138:139], v[26:27]
	v_pk_mul_f32 v[110:111], v[76:77], v[120:121] op_sel_hi:[0,1]
	v_addc_co_u32_e32 v119, vcc, 0, v129, vcc
	v_pk_fma_f32 v[34:35], v[138:139], v[110:111], v[34:35]
	v_pk_fma_f32 v[32:33], v[136:137], v[36:37], v[32:33]
	v_pk_mul_f32 v[36:37], v[82:83], v[122:123] op_sel_hi:[0,1]
	v_pk_mul_f32 v[110:111], v[82:83], v[124:125] op_sel_hi:[0,1]
	v_add_co_u32_e32 v120, vcc, s24, v128
	v_pk_fma_f32 v[30:31], v[138:139], v[110:111], v[30:31]
	v_pk_fma_f32 v[28:29], v[136:137], v[36:37], v[28:29]
	v_addc_co_u32_e32 v121, vcc, 0, v129, vcc
	global_store_dwordx4 v[128:129], v[20:23], off sc0 sc1 nt
	global_store_dwordx4 v[118:119], v[24:27], off offset:-4096 sc0 sc1 nt
	global_store_dwordx4 v[118:119], v[32:35], off sc0 sc1 nt
	global_store_dwordx4 v[120:121], v[28:31], off sc0 sc1 nt
	s_nop 1
	v_mov_b32_e32 v110, v160
	v_mov_b32_e32 v111, v161
	v_mov_b32_e32 v112, v162
	v_mov_b32_e32 v113, v163
	v_mov_b32_e32 v36, v39
	v_mov_b32_e32 v37, v41
	v_pk_mul_f32 v[36:37], v[56:57], v[36:37] op_sel_hi:[0,1]
	v_mov_b32_e32 v39, v40
	v_pk_mul_f32 v[38:39], v[56:57], v[38:39] op_sel_hi:[0,1]
	v_mov_b32_e32 v40, v115
	v_mov_b32_e32 v41, v117
	v_mov_b32_e32 v115, v116
	v_add_co_u32_e32 v122, vcc, s22, v128
	v_mov_b32_e32 v62, v87
	s_nop 0
	v_addc_co_u32_e32 v123, vcc, 0, v129, vcc
	v_pk_mul_f32 v[86:87], v[56:57], v[88:89] op_sel_hi:[0,1]
	v_pk_mul_f32 v[62:63], v[56:57], v[62:63] op_sel_hi:[0,1]
	v_mov_b32_e32 v56, v59
	v_pk_mul_f32 v[88:89], v[58:59], v[60:61] op_sel_hi:[0,1]
	s_andn2_b64 vcc, exec, s[30:31]
	v_pk_fma_f32 v[14:15], v[36:37], v[112:113], v[14:15]
	v_mov_b32_e32 v36, v43
	v_mov_b32_e32 v37, v95
	v_pk_mul_f32 v[36:37], v[58:59], v[36:37] op_sel_hi:[0,1]
	v_mov_b32_e32 v43, v94
	v_pk_fma_f32 v[12:13], v[38:39], v[110:111], v[12:13]
	v_pk_mul_f32 v[38:39], v[58:59], v[42:43] op_sel_hi:[0,1]
	v_pk_fma_f32 v[18:19], v[36:37], v[112:113], v[18:19]
	v_mov_b32_e32 v36, v105
	v_mov_b32_e32 v37, v107
	v_mov_b32_e32 v105, v106
	v_pk_fma_f32 v[16:17], v[38:39], v[110:111], v[16:17]
	v_pk_mul_f32 v[38:39], v[76:77], v[36:37] op_sel_hi:[0,1]
	v_pk_mul_f32 v[36:37], v[76:77], v[104:105] op_sel_hi:[0,1]
	v_pk_mul_f32 v[42:43], v[82:83], v[40:41] op_sel_hi:[0,1]
	v_pk_mul_f32 v[40:41], v[82:83], v[114:115] op_sel_hi:[0,1]
	v_pk_fma_f32 v[36:37], v[110:111], v[36:37], v[140:141]
	v_pk_fma_f32 v[38:39], v[112:113], v[38:39], v[142:143]
	v_pk_fma_f32 v[40:41], v[110:111], v[40:41], v[100:101]
	v_pk_fma_f32 v[42:43], v[112:113], v[42:43], v[102:103]
	global_store_dwordx4 v[128:129], v[12:15], off offset:1024 sc0 sc1 nt
	global_store_dwordx4 v[122:123], v[16:19], off offset:1024 sc0 sc1 nt
	global_store_dwordx4 v[118:119], v[36:39], off offset:1024 sc0 sc1 nt
	global_store_dwordx4 v[120:121], v[40:43], off offset:1024 sc0 sc1 nt
	s_nop 1
	v_mov_b32_e32 v100, v164
	v_mov_b32_e32 v101, v165
	v_mov_b32_e32 v102, v166
	v_mov_b32_e32 v103, v167
	v_pk_fma_f32 v[4:5], v[48:49], v[100:101], v[4:5]
	v_pk_fma_f32 v[6:7], v[50:51], v[102:103], v[6:7]
	v_pk_mul_f32 v[48:49], v[58:59], v[92:93] op_sel_hi:[0,1]
	v_pk_mul_f32 v[50:51], v[58:59], v[90:91] op_sel_hi:[0,1]
	v_pk_fma_f32 v[8:9], v[50:51], v[100:101], v[8:9]
	v_pk_fma_f32 v[10:11], v[48:49], v[102:103], v[10:11]
	v_pk_mul_f32 v[48:49], v[76:77], v[98:99] op_sel_hi:[0,1]
	v_pk_mul_f32 v[50:51], v[76:77], v[96:97] op_sel_hi:[0,1]
	v_pk_fma_f32 v[44:45], v[50:51], v[100:101], v[44:45]
	v_pk_fma_f32 v[46:47], v[48:49], v[102:103], v[46:47]
	v_pk_mul_f32 v[50:51], v[82:83], v[126:127] op_sel_hi:[0,1]
	v_pk_mul_f32 v[48:49], v[82:83], v[108:109] op_sel_hi:[0,1]
	v_pk_fma_f32 v[48:49], v[100:101], v[48:49], v[144:145]
	v_pk_fma_f32 v[50:51], v[102:103], v[50:51], v[146:147]
	global_store_dwordx4 v[128:129], v[4:7], off offset:2048 sc0 sc1 nt
	global_store_dwordx4 v[122:123], v[8:11], off offset:2048 sc0 sc1 nt
	global_store_dwordx4 v[118:119], v[44:47], off offset:2048 sc0 sc1 nt
	global_store_dwordx4 v[120:121], v[48:51], off offset:2048 sc0 sc1 nt
	s_nop 1
	v_mov_b32_e32 v90, v168
	v_mov_b32_e32 v91, v169
	v_mov_b32_e32 v92, v170
	v_mov_b32_e32 v93, v171
	v_pk_fma_f32 v[60:61], v[62:63], v[90:91], v[0:1]
	v_pk_mul_f32 v[0:1], v[58:59], v[56:57] op_sel_hi:[0,1]
	v_pk_fma_f32 v[62:63], v[86:87], v[92:93], v[2:3]
	v_pk_fma_f32 v[56:57], v[0:1], v[90:91], v[52:53]
	v_pk_mul_f32 v[0:1], v[76:77], v[78:79] op_sel_hi:[0,1]
	v_pk_mul_f32 v[2:3], v[76:77], v[74:75] op_sel_hi:[0,1]
	v_pk_fma_f32 v[58:59], v[88:89], v[92:93], v[54:55]
	v_pk_fma_f32 v[52:53], v[2:3], v[90:91], v[64:65]
	v_pk_fma_f32 v[54:55], v[0:1], v[92:93], v[66:67]
	v_pk_mul_f32 v[2:3], v[82:83], v[84:85] op_sel_hi:[0,1]
	v_pk_mul_f32 v[0:1], v[82:83], v[80:81] op_sel_hi:[0,1]
	v_pk_fma_f32 v[0:1], v[0:1], v[90:91], v[148:149]
	v_pk_fma_f32 v[2:3], v[2:3], v[92:93], v[150:151]
	global_store_dwordx4 v[128:129], v[60:63], off offset:3072 sc0 sc1 nt
	global_store_dwordx4 v[122:123], v[56:59], off offset:3072 sc0 sc1 nt
	global_store_dwordx4 v[118:119], v[52:55], off offset:3072 sc0 sc1 nt
	global_store_dwordx4 v[120:121], v[0:3], off offset:3072 sc0 sc1 nt
	s_cbranch_vccnz .LBB0_208
; __device__ __forceinline__ void ew_post(const bf16* Y, const float* xin, float* xout, const float* gpost, const float* gnext, bf16* H, int gw, int ngw, int lane) {
;     ...
;                 s2[q] += (xv[q][j].x * xv[q][j].x + xv[q][j].y * xv[q][j].y) + (xv[q][j].z * xv[q][j].z + xv[q][j].w * xv[q][j].w); } }
;         if (gnext) {
;             float r2[EW_NR];
; #pragma unroll
;             for (int q = 0; q < EW_NR; ++q) r2[q] = rsqrtf(wave_sum(s2[q]) * (1.f / DM) + RMS_EPS);
	v_pk_mul_f32 v[64:65], v[30:31], v[30:31]
	v_pk_mul_f32 v[66:67], v[28:29], v[28:29]
	v_mul_f32_e32 v78, v1, v1
	v_pk_mov_b32 v[74:75], v[66:67], v[64:65] op_sel:[1,0]
	v_mov_b32_e32 v67, v65
	v_pk_add_f32 v[64:65], v[74:75], v[66:67]
	v_pk_mul_f32 v[66:67], v[42:43], v[42:43]
	v_pk_mul_f32 v[74:75], v[40:41], v[40:41]
	v_mul_f32_e32 v79, v2, v2
	v_pk_mov_b32 v[76:77], v[74:75], v[66:67] op_sel:[1,0]
	v_mov_b32_e32 v75, v67
	v_pk_add_f32 v[66:67], v[76:77], v[74:75]
	v_mul_f32_e32 v74, v49, v49
	v_mul_f32_e32 v76, v0, v0
	v_pk_fma_f32 v[74:75], v[48:49], v[48:49], v[74:75] op_sel_hi:[1,1,0]
	v_mul_f32_e32 v80, v3, v3
	v_mov_b32_e32 v75, v76
	v_mul_f32_e32 v76, v51, v51
	v_pk_fma_f32 v[76:77], v[50:51], v[50:51], v[76:77] op_sel_hi:[1,1,0]
	v_pk_add_f32 v[64:65], v[64:65], v[64:65] op_sel:[0,1] op_sel_hi:[1,0]
	v_pk_add_f32 v[66:67], v[66:67], v[66:67] op_sel:[0,1] op_sel_hi:[1,0]
	v_mov_b32_e32 v77, v78
	v_mov_b32_e32 v65, v79
	v_mov_b32_e32 v67, v80
	v_pk_add_f32 v[74:75], v[74:75], v[76:77]
	v_pk_add_f32 v[64:65], v[64:65], v[66:67]
	v_pk_mul_f32 v[66:67], v[34:35], v[34:35]
	v_pk_add_f32 v[64:65], v[74:75], v[64:65]
	v_pk_mul_f32 v[74:75], v[32:33], v[32:33]
	v_mul_f32_e32 v86, v53, v53
	v_pk_mov_b32 v[76:77], v[74:75], v[66:67] op_sel:[1,0]
	v_mov_b32_e32 v75, v67
	v_pk_add_f32 v[66:67], v[76:77], v[74:75]
	v_pk_mul_f32 v[74:75], v[38:39], v[38:39]
	v_pk_mul_f32 v[76:77], v[36:37], v[36:37]
	v_pk_add_f32 v[66:67], v[66:67], v[66:67] op_sel:[0,1] op_sel_hi:[1,0]
	v_pk_mov_b32 v[78:79], v[76:77], v[74:75] op_sel:[1,0]
	v_mov_b32_e32 v77, v75
	v_pk_add_f32 v[74:75], v[78:79], v[76:77]
	v_mul_f32_e32 v76, v52, v52
	v_mov_b32_e32 v67, v76
	v_pk_mul_f32 v[76:77], v[26:27], v[26:27]
	v_pk_mul_f32 v[78:79], v[24:25], v[24:25]
	v_mul_f32_e32 v87, v54, v54
	v_pk_mov_b32 v[80:81], v[78:79], v[76:77] op_sel:[1,0]
	v_mov_b32_e32 v79, v77
	v_pk_add_f32 v[76:77], v[80:81], v[78:79]
	v_pk_mul_f32 v[78:79], v[18:19], v[18:19]
	v_pk_mul_f32 v[80:81], v[16:17], v[16:17]
	v_pk_add_f32 v[76:77], v[76:77], v[76:77] op_sel:[0,1] op_sel_hi:[1,0]
	v_pk_mov_b32 v[82:83], v[80:81], v[78:79] op_sel:[1,0]
	v_mov_b32_e32 v81, v79
	v_pk_add_f32 v[78:79], v[82:83], v[80:81]
	v_mul_f32_e32 v80, v56, v56
	v_mul_f32_e32 v81, v57, v57
	v_pk_add_f32 v[78:79], v[78:79], v[78:79] op_sel:[0,1] op_sel_hi:[1,0]
	v_mov_b32_e32 v77, v80
	v_mov_b32_e32 v79, v81
	v_pk_add_f32 v[76:77], v[76:77], v[78:79]
	v_mul_f32_e32 v78, v9, v9
	v_mul_f32_e32 v80, v11, v11
	v_mul_f32_e32 v82, v58, v58
	v_mul_f32_e32 v83, v59, v59
	v_pk_fma_f32 v[78:79], v[8:9], v[8:9], v[78:79] op_sel_hi:[1,1,0]
	v_pk_fma_f32 v[80:81], v[10:11], v[10:11], v[80:81] op_sel_hi:[1,1,0]
	v_mov_b32_e32 v79, v82
	v_mov_b32_e32 v81, v83
	v_pk_add_f32 v[78:79], v[78:79], v[80:81]
	v_pk_mul_f32 v[80:81], v[20:21], v[20:21]
	v_pk_add_f32 v[76:77], v[76:77], v[78:79]
	v_pk_mul_f32 v[78:79], v[22:23], v[22:23]
	v_mul_f32_e32 v88, v55, v55
	v_pk_mov_b32 v[82:83], v[80:81], v[78:79] op_sel:[1,0]
	v_mov_b32_e32 v81, v79
	v_pk_add_f32 v[78:79], v[82:83], v[80:81]
	v_pk_mul_f32 v[80:81], v[14:15], v[14:15]
	v_pk_mul_f32 v[82:83], v[12:13], v[12:13]
	v_pk_add_f32 v[78:79], v[78:79], v[78:79] op_sel:[0,1] op_sel_hi:[1,0]
	v_pk_mov_b32 v[84:85], v[82:83], v[80:81] op_sel:[1,0]
	v_mov_b32_e32 v83, v81
	v_pk_add_f32 v[80:81], v[84:85], v[82:83]
	v_mul_f32_e32 v82, v60, v60
	v_mul_f32_e32 v83, v61, v61
	v_pk_add_f32 v[80:81], v[80:81], v[80:81] op_sel:[0,1] op_sel_hi:[1,0]
	v_mov_b32_e32 v79, v82
	v_mov_b32_e32 v81, v83
	v_pk_add_f32 v[78:79], v[78:79], v[80:81]
	v_mul_f32_e32 v80, v5, v5
	v_mul_f32_e32 v82, v7, v7
	v_mul_f32_e32 v84, v62, v62
	v_mul_f32_e32 v85, v63, v63
	v_pk_fma_f32 v[80:81], v[4:5], v[4:5], v[80:81] op_sel_hi:[1,1,0]
	v_pk_fma_f32 v[82:83], v[6:7], v[6:7], v[82:83] op_sel_hi:[1,1,0]
	v_mov_b32_e32 v81, v84
	v_mov_b32_e32 v83, v85
	v_pk_add_f32 v[80:81], v[80:81], v[82:83]
	v_pk_add_f32 v[82:83], v[74:75], v[74:75] op_sel:[0,1] op_sel_hi:[1,0]
	v_pk_add_f32 v[78:79], v[78:79], v[80:81]
	v_mov_b32_e32 v80, v76
	v_mov_b32_e32 v81, v78
	v_mov_b32_e32 v78, v77
	s_nop 1
	v_mov_b32_e32 v74, v232
	v_mov_b32_e32 v75, v233
	v_mov_b32_e32 v76, v234
	v_mov_b32_e32 v77, v235
	v_pk_add_f32 v[78:79], v[80:81], v[78:79]
	v_mov_b32_e32 v83, v86
	ds_bpermute_b32 v81, v130, v79
	ds_bpermute_b32 v80, v130, v78
	v_pk_add_f32 v[66:67], v[66:67], v[82:83]
	v_mul_f32_e32 v82, v45, v45
	v_mul_f32_e32 v84, v47, v47
	v_pk_fma_f32 v[82:83], v[44:45], v[44:45], v[82:83] op_sel_hi:[1,1,0]
	v_pk_fma_f32 v[84:85], v[46:47], v[46:47], v[84:85] op_sel_hi:[1,1,0]
	v_mov_b32_e32 v83, v87
	v_mov_b32_e32 v85, v88
	v_pk_add_f32 v[82:83], v[82:83], v[84:85]
	s_waitcnt lgkmcnt(0)
	v_pk_add_f32 v[78:79], v[78:79], v[80:81]
	v_pk_add_f32 v[66:67], v[66:67], v[82:83]
	v_mov_b32_e32 v82, v64
	v_mov_b32_e32 v83, v66
	v_mov_b32_e32 v66, v65
	ds_bpermute_b32 v81, v131, v79
	ds_bpermute_b32 v80, v131, v78
	v_pk_add_f32 v[64:65], v[82:83], v[66:67]
	ds_bpermute_b32 v67, v130, v65
	ds_bpermute_b32 v66, v130, v64
	s_waitcnt lgkmcnt(2)
	v_pk_add_f32 v[78:79], v[78:79], v[80:81]
	ds_bpermute_b32 v81, v132, v79
	ds_bpermute_b32 v80, v132, v78
	s_waitcnt lgkmcnt(2)
	v_pk_add_f32 v[64:65], v[64:65], v[66:67]
	ds_bpermute_b32 v67, v131, v65
	ds_bpermute_b32 v66, v131, v64
	s_waitcnt lgkmcnt(2)
	v_pk_add_f32 v[78:79], v[78:79], v[80:81]
	ds_bpermute_b32 v81, v133, v79
	ds_bpermute_b32 v80, v133, v78
	s_waitcnt lgkmcnt(2)
	v_pk_add_f32 v[64:65], v[64:65], v[66:67]
	ds_bpermute_b32 v67, v132, v65
	ds_bpermute_b32 v66, v132, v64
	s_waitcnt lgkmcnt(2)
	v_pk_add_f32 v[78:79], v[78:79], v[80:81]
	ds_bpermute_b32 v81, v134, v79
	ds_bpermute_b32 v80, v134, v78
	s_waitcnt lgkmcnt(2)
; __device__ __forceinline__ float wave_sum(float v) {
; #pragma unroll
;     for (int o = 1; o < 64; o <<= 1) v += __shfl_xor(v, o);
;     return v;
; }
; __device__ __forceinline__ void ew_post(const bf16* Y, const float* xin, float* xout, const float* gpost, const float* gnext, bf16* H, int gw, int ngw, int lane) {
;     ...
;             for (int q = 0; q < EW_NR; ++q) r2[q] = rsqrtf(wave_sum(s2[q]) * (1.f / DM) + RMS_EPS);
	v_pk_add_f32 v[64:65], v[64:65], v[66:67]
	ds_bpermute_b32 v67, v133, v65
	ds_bpermute_b32 v66, v133, v64
	s_waitcnt lgkmcnt(2)
	v_pk_add_f32 v[78:79], v[78:79], v[80:81]
	ds_bpermute_b32 v81, v135, v79
	ds_bpermute_b32 v80, v135, v78
	s_waitcnt lgkmcnt(2)
	v_pk_add_f32 v[64:65], v[64:65], v[66:67]
	ds_bpermute_b32 v67, v134, v65
	ds_bpermute_b32 v66, v134, v64
	s_waitcnt lgkmcnt(2)
	v_pk_add_f32 v[78:79], v[78:79], v[80:81]
	v_mov_b64_e32 v[80:81], s[26:27]
	v_pk_fma_f32 v[78:79], v[78:79], s[44:45], v[80:81] op_sel_hi:[1,0,0]
	s_waitcnt lgkmcnt(0)
	v_pk_add_f32 v[64:65], v[64:65], v[66:67]
	v_mul_f32_e32 v82, 0x4b800000, v79
	v_cmp_gt_f32_e32 vcc, s3, v79
	ds_bpermute_b32 v67, v135, v65
	ds_bpermute_b32 v66, v135, v64
	v_cndmask_b32_e32 v79, v79, v82, vcc
	v_rsq_f32_e32 v79, v79
	v_mul_f32_e32 v82, 0x4b800000, v78
	v_cmp_gt_f32_e64 s[4:5], s3, v78
	s_waitcnt lgkmcnt(0)
; __device__ __forceinline__ unsigned pk2(float lo, float hi) { f32v2 v = {lo, hi}; bf16v2 r = __builtin_convertvector(v, bf16v2); return __builtin_bit_cast(unsigned, r); }
; __device__ __forceinline__ void ew_post(const bf16* Y, const float* xin, float* xout, const float* gpost, const float* gnext, bf16* H, int gw, int ngw, int lane) {
;     ...
;             for (int q = 0; q < EW_NR; ++q) r2[q] = rsqrtf(wave_sum(s2[q]) * (1.f / DM) + RMS_EPS);
; #pragma unroll
;             for (int j = 0; j < 4; ++j) { const f32x4 g = *((const f32x4*)gnext + lane + 64 * j);
; #pragma unroll
;                 for (int q = 0; q < EW_NR; ++q) { v2u w; w.x = pk2(xv[q][j].x * r2[q] * g.x, xv[q][j].y * r2[q] * g.y); w.y = pk2(xv[q][j].z * r2[q] * g.z, xv[q][j].w * r2[q] * g.w);
;                     *((v2u*)(H + (size_t)(m0 + q) * DM) + lane + 64 * j) = w; } }
	v_pk_add_f32 v[64:65], v[64:65], v[66:67]
	v_cndmask_b32_e64 v78, v78, v82, s[4:5]
	v_rsq_f32_e32 v82, v78
	v_mul_f32_e32 v78, 0x45800000, v79
	v_pk_fma_f32 v[64:65], v[64:65], s[44:45], v[80:81] op_sel_hi:[1,0,0]
	v_cndmask_b32_e32 v78, v79, v78, vcc
	v_mul_f32_e32 v66, 0x4b800000, v65
	v_cmp_gt_f32_e32 vcc, s3, v65
	v_mul_f32_e32 v79, 0x45800000, v82
	v_cmp_gt_f32_e64 s[6:7], s3, v64
	v_cndmask_b32_e32 v65, v65, v66, vcc
	v_rsq_f32_e32 v65, v65
	v_mul_f32_e32 v66, 0x4b800000, v64
	v_pk_mul_f32 v[20:21], v[20:21], v[78:79] op_sel_hi:[1,0]
	v_pk_mul_f32 v[22:23], v[22:23], v[78:79] op_sel_hi:[1,0]
	v_mul_f32_e32 v67, 0x45800000, v65
	v_cndmask_b32_e64 v64, v64, v66, s[6:7]
	v_cndmask_b32_e64 v66, v82, v79, s[4:5]
	v_cndmask_b32_e32 v80, v65, v67, vcc
	v_pk_mul_f32 v[20:21], v[20:21], v[74:75]
	v_pk_mul_f32 v[22:23], v[22:23], v[76:77]
	v_add_co_u32_e32 v82, vcc, s20, v72
	v_cvt_pk_bf16_f32 v20, v20, v21
	v_cvt_pk_bf16_f32 v21, v22, v23
	v_addc_co_u32_e32 v83, vcc, -1, v73, vcc
	v_rsq_f32_e32 v64, v64
	global_store_dwordx2 v[82:83], v[20:21], off offset:-3584
	v_pk_mul_f32 v[20:21], v[24:25], v[66:67] op_sel_hi:[1,0]
	v_pk_mul_f32 v[22:23], v[26:27], v[66:67] op_sel_hi:[1,0]
	v_pk_mul_f32 v[20:21], v[20:21], v[74:75]
	v_pk_mul_f32 v[22:23], v[22:23], v[76:77]
	v_cvt_pk_bf16_f32 v20, v20, v21
	v_cvt_pk_bf16_f32 v21, v22, v23
	global_store_dwordx2 v[82:83], v[20:21], off offset:-1536
	v_pk_mul_f32 v[20:21], v[32:33], v[80:81] op_sel_hi:[1,0]
	v_pk_mul_f32 v[22:23], v[34:35], v[80:81] op_sel_hi:[1,0]
	v_mul_f32_e32 v65, 0x45800000, v64
	v_pk_mul_f32 v[20:21], v[74:75], v[20:21]
	v_pk_mul_f32 v[22:23], v[76:77], v[22:23]
	v_add_co_u32_e32 v24, vcc, s21, v72
	v_cndmask_b32_e64 v64, v64, v65, s[6:7]
	v_cvt_pk_bf16_f32 v20, v20, v21
	v_cvt_pk_bf16_f32 v21, v22, v23
	v_addc_co_u32_e32 v25, vcc, -1, v73, vcc
	global_store_dwordx2 v[24:25], v[20:21], off offset:-3584
	v_pk_mul_f32 v[20:21], v[28:29], v[64:65] op_sel_hi:[1,0]
	v_pk_mul_f32 v[22:23], v[30:31], v[64:65] op_sel_hi:[1,0]
	v_pk_mul_f32 v[20:21], v[74:75], v[20:21]
	v_pk_mul_f32 v[22:23], v[76:77], v[22:23]
	v_cvt_pk_bf16_f32 v20, v20, v21
	v_cvt_pk_bf16_f32 v21, v22, v23
	global_store_dwordx2 v[24:25], v[20:21], off offset:-1536
	s_nop 1
	v_mov_b32_e32 v20, v236
	v_mov_b32_e32 v21, v237
	v_mov_b32_e32 v22, v238
	v_mov_b32_e32 v23, v239
	v_pk_mul_f32 v[12:13], v[12:13], v[78:79] op_sel_hi:[1,0]
	v_pk_mul_f32 v[14:15], v[14:15], v[78:79] op_sel_hi:[1,0]
	v_pk_mul_f32 v[4:5], v[4:5], v[78:79] op_sel_hi:[1,0]
	v_pk_mul_f32 v[6:7], v[6:7], v[78:79] op_sel_hi:[1,0]
	v_pk_mul_f32 v[0:1], v[0:1], v[64:65] op_sel_hi:[1,0]
	v_pk_mul_f32 v[2:3], v[2:3], v[64:65] op_sel_hi:[1,0]
	v_pk_mul_f32 v[12:13], v[12:13], v[20:21]
	v_pk_mul_f32 v[14:15], v[14:15], v[22:23]
	v_cvt_pk_bf16_f32 v12, v12, v13
	v_cvt_pk_bf16_f32 v13, v14, v15
	global_store_dwordx2 v[82:83], v[12:13], off offset:-3072
	v_pk_mul_f32 v[12:13], v[16:17], v[66:67] op_sel_hi:[1,0]
	v_pk_mul_f32 v[14:15], v[18:19], v[66:67] op_sel_hi:[1,0]
	v_pk_mul_f32 v[12:13], v[12:13], v[20:21]
	v_pk_mul_f32 v[14:15], v[14:15], v[22:23]
	v_cvt_pk_bf16_f32 v12, v12, v13
	v_cvt_pk_bf16_f32 v13, v14, v15
	global_store_dwordx2 v[82:83], v[12:13], off offset:-1024
	v_pk_mul_f32 v[12:13], v[36:37], v[80:81] op_sel_hi:[1,0]
	v_pk_mul_f32 v[14:15], v[38:39], v[80:81] op_sel_hi:[1,0]
	v_pk_mul_f32 v[12:13], v[12:13], v[20:21]
	v_pk_mul_f32 v[14:15], v[14:15], v[22:23]
	v_cvt_pk_bf16_f32 v12, v12, v13
	v_cvt_pk_bf16_f32 v13, v14, v15
	global_store_dwordx2 v[24:25], v[12:13], off offset:-3072
	v_pk_mul_f32 v[12:13], v[40:41], v[64:65] op_sel_hi:[1,0]
	v_pk_mul_f32 v[14:15], v[42:43], v[64:65] op_sel_hi:[1,0]
	v_pk_mul_f32 v[12:13], v[20:21], v[12:13]
	v_pk_mul_f32 v[14:15], v[22:23], v[14:15]
	v_cvt_pk_bf16_f32 v12, v12, v13
	v_cvt_pk_bf16_f32 v13, v14, v15
	global_store_dwordx2 v[24:25], v[12:13], off offset:-1024
	s_nop 1
	v_mov_b32_e32 v12, v240
	v_mov_b32_e32 v13, v241
	v_mov_b32_e32 v14, v242
	v_mov_b32_e32 v15, v243
	v_pk_mul_f32 v[16:17], v[52:53], v[80:81] op_sel_hi:[1,0]
	v_pk_mul_f32 v[18:19], v[54:55], v[80:81] op_sel_hi:[1,0]
	v_pk_mul_f32 v[4:5], v[4:5], v[12:13]
	v_pk_mul_f32 v[6:7], v[6:7], v[14:15]
	v_cvt_pk_bf16_f32 v4, v4, v5
	v_cvt_pk_bf16_f32 v5, v6, v7
	global_store_dwordx2 v[82:83], v[4:5], off offset:-2560
	v_pk_mul_f32 v[4:5], v[8:9], v[66:67] op_sel_hi:[1,0]
	v_pk_mul_f32 v[6:7], v[10:11], v[66:67] op_sel_hi:[1,0]
	v_pk_mul_f32 v[4:5], v[4:5], v[12:13]
	v_pk_mul_f32 v[6:7], v[6:7], v[14:15]
	v_cvt_pk_bf16_f32 v4, v4, v5
	v_cvt_pk_bf16_f32 v5, v6, v7
	global_store_dwordx2 v[82:83], v[4:5], off offset:-512
	v_pk_mul_f32 v[4:5], v[44:45], v[80:81] op_sel_hi:[1,0]
	v_pk_mul_f32 v[6:7], v[46:47], v[80:81] op_sel_hi:[1,0]
	v_pk_mul_f32 v[4:5], v[4:5], v[12:13]
	v_pk_mul_f32 v[6:7], v[6:7], v[14:15]
	v_cvt_pk_bf16_f32 v4, v4, v5
	v_cvt_pk_bf16_f32 v5, v6, v7
	global_store_dwordx2 v[24:25], v[4:5], off offset:-2560
	v_pk_mul_f32 v[4:5], v[48:49], v[64:65] op_sel_hi:[1,0]
	v_pk_mul_f32 v[6:7], v[50:51], v[64:65] op_sel_hi:[1,0]
	v_pk_mul_f32 v[4:5], v[4:5], v[12:13]
	v_pk_mul_f32 v[6:7], v[6:7], v[14:15]
	v_cvt_pk_bf16_f32 v4, v4, v5
	v_cvt_pk_bf16_f32 v5, v6, v7
	global_store_dwordx2 v[24:25], v[4:5], off offset:-512
	s_nop 1
	v_mov_b32_e32 v4, v244
	v_mov_b32_e32 v5, v245
	v_mov_b32_e32 v6, v246
	v_mov_b32_e32 v7, v247
	v_pk_mul_f32 v[8:9], v[60:61], v[78:79] op_sel_hi:[1,0]
	v_pk_mul_f32 v[10:11], v[62:63], v[78:79] op_sel_hi:[1,0]
	v_pk_mul_f32 v[12:13], v[56:57], v[66:67] op_sel_hi:[1,0]
	v_pk_mul_f32 v[14:15], v[58:59], v[66:67] op_sel_hi:[1,0]
	v_pk_mul_f32 v[8:9], v[8:9], v[4:5]
	v_pk_mul_f32 v[10:11], v[10:11], v[6:7]
	v_pk_mul_f32 v[12:13], v[12:13], v[4:5]
	v_pk_mul_f32 v[14:15], v[14:15], v[6:7]
	v_pk_mul_f32 v[16:17], v[16:17], v[4:5]
	v_pk_mul_f32 v[18:19], v[18:19], v[6:7]
	v_pk_mul_f32 v[0:1], v[0:1], v[4:5]
	v_pk_mul_f32 v[2:3], v[2:3], v[6:7]
	v_cvt_pk_bf16_f32 v4, v8, v9
	v_cvt_pk_bf16_f32 v5, v10, v11
	v_cvt_pk_bf16_f32 v6, v12, v13
	v_cvt_pk_bf16_f32 v7, v14, v15
	v_cvt_pk_bf16_f32 v8, v16, v17
	v_cvt_pk_bf16_f32 v9, v18, v19
	v_cvt_pk_bf16_f32 v0, v0, v1
	v_cvt_pk_bf16_f32 v1, v2, v3
	global_store_dwordx2 v[82:83], v[4:5], off offset:-2048
	global_store_dwordx2 v[24:25], v[6:7], off offset:-4096
	global_store_dwordx2 v[24:25], v[8:9], off offset:-2048
	global_store_dwordx2 v[24:25], v[0:1], off
	s_branch .LBB0_208
